# v15: v12 + preheader waits removed + ret_out Q re-reads batched + ret_scan loads before stores + LN1 next-row prefetch
# baseline (speedup 1.0000x reference)
; #define LAS __attribute__((address_space(3)))
; __device__ __forceinline__ float ret_log_gamma(const float* dexp, int dir, int h) { return log1pf(-exp2f(-dexp[dir * 8 + h])); }
; __device__ __forceinline__ void ret_scan(const bf16* proj, bf16* ST, bf16* FS, const float* dexp, LAS unsigned char* lds, int vb, int nb, int tid_in, int wave) {
;     LAS unsigned char* Kt = lds;
;     LAS unsigned char* Vt = lds + 34816;
;     for (int c = vb; c < 384; c += nb) {
;         int tid = tid_in; asm volatile("" : "+v"(tid));
;         const int lane = tid & 63, g = lane >> 4, qi = lane & 15;
;         const int vs = c >> 5, h = (c >> 2) & 7, dir = (c >> 1) & 1, dsl = c & 1;
;         const bool seg = vs >= 8;
;         const int base = seg ? 16384 + (vs - 8) * 2048 : vs * 2048, N = 16, nsteps = seg ? 16 : 15;
;         const float lg = ret_log_gamma(dexp, dir, h), gC = expf(128.0f * lg);
.LBB0_413:
	s_ashr_i32 s5, s46, 5
	s_bfe_u32 s47, s46, 0x30002
	s_bfe_i32 s42, s46, 0x10001
	s_bfe_u32 s4, s46, 0x10001
	s_cmp_gt_i32 s5, 7
	s_cselect_b32 s52, 16, 15
	s_lshl_b32 s30, s47, 2
	s_lshl_b32 s31, s4, 5
	s_or_b32 s30, s31, s30
	v_mov_b32_e32 v102, v146
	v_mov_b32_e32 v1, s30
	global_load_dword v2, v1, s[16:17]
	s_mov_b32 s30, 0x42fc0000
	s_waitcnt vmcnt(12)
	v_lshlrev_b32_e32 v3, 3, v102
	v_and_b32_e32 v114, 0x78, v3
	v_and_b32_e32 v116, 0xf8, v3
	v_ashrrev_i32_e32 v1, 4, v102
	v_add_u32_e32 v65, 0xe00, v102
	v_ashrrev_i32_e32 v181, 5, v65
	v_add_u32_e32 v64, 0xc00, v102
	s_waitcnt vmcnt(2)
	v_mov_b64_e32 v[42:43], s[6:7]
	v_ashrrev_i32_e32 v180, 5, v64
	v_add_u32_e32 v63, 0xa00, v102
	v_lshlrev_b32_e32 v182, 1, v116
	v_add_u32_e32 v19, 0x200, v102
	v_ashrrev_i32_e32 v179, 5, v63
	v_ashrrev_i32_e32 v147, 4, v19
	v_add_u32_e32 v62, 0x800, v102
	v_ashrrev_i32_e32 v178, 5, v62
	v_add_u32_e32 v17, 0x600, v102
	v_ashrrev_i32_e32 v175, 5, v19
	v_ashrrev_i32_e32 v177, 5, v17
	v_add_u32_e32 v18, 0x400, v102
	v_ashrrev_i32_e32 v176, 5, v18
	v_ashrrev_i32_e32 v173, 4, v17
	v_ashrrev_i32_e32 v172, 4, v18
	v_ashrrev_i32_e32 v174, 5, v102
	s_movk_i32 s59, 0x440
	v_bfe_u32 v110, v102, 4, 2
	v_add_u32_e32 v115, s44, v114
	v_add_u32_e32 v117, 0, v114
	v_lshl_or_b32 v111, v110, 1, 8
	v_mad_u32_u24 v103, v111, s59, v117
	v_and_b32_e32 v149, 15, v102
	v_mul_u32_u24_e32 v210, 0x1080, v110
	s_waitcnt vmcnt(0)
	v_cmp_lt_f32_e32 vcc, s30, v2
	s_nop 1
	v_cndmask_b32_e32 v3, 0, v219, vcc
	s_and_b64 s[30:31], vcc, exec
	v_sub_f32_e32 v2, v3, v2
	s_cselect_b32 s36, 0xffffffc0, 0
	s_lshl_b32 s53, s5, 11
	s_lshl_b32 s5, s5, 3
	v_exp_f32_e32 v2, v2
	s_lshl_b32 s30, s46, 7
	s_or_b32 s5, s5, s47
	s_and_b32 s64, s30, 0x80
	s_sub_i32 s30, s5, 64
	s_ashr_i32 s31, s30, 31
	s_lshl_b32 s43, s47, 8
	s_lshl_b64 s[30:31], s[30:31], 18
	v_ldexp_f32 v16, v2, s36
	s_add_u32 s5, s28, s30
	v_sub_f32_e32 v4, 1.0, v16
	s_addc_u32 s30, s29, s31
	s_lshl_b32 s31, s4, 17
	v_add_f32_e32 v5, -1.0, v4
	v_frexp_mant_f32_e32 v6, v4
	v_cvt_f64_f32_e32 v[2:3], v4
	s_add_u32 s54, s5, s31
	s_mov_b32 s5, 0x3f2aaaab
	v_sub_f32_e32 v7, v5, v4
	v_frexp_exp_i32_f64_e32 v2, v[2:3]
	v_cmp_gt_f32_e32 vcc, s5, v6
	v_sub_f32_e64 v5, -v16, v5
	v_add_f32_e32 v3, 1.0, v7
	v_subbrev_co_u32_e32 v2, vcc, 0, v2, vcc
	v_add_f32_e32 v3, v5, v3
	v_sub_u32_e32 v5, 0, v2
	v_ldexp_f32 v4, v4, v5
	v_add_f32_e32 v6, -1.0, v4
	v_add_f32_e32 v7, 1.0, v4
	v_ldexp_f32 v3, v3, v5
	v_add_f32_e32 v5, 1.0, v6
	v_add_f32_e32 v8, -1.0, v7
	v_sub_f32_e32 v5, v4, v5
	v_sub_f32_e32 v4, v4, v8
	v_add_f32_e32 v8, v3, v5
	v_add_f32_e32 v3, v3, v4
	v_add_f32_e32 v10, v7, v3
	v_rcp_f32_e32 v11, v10
	v_add_f32_e32 v5, v6, v8
	v_sub_f32_e32 v6, v5, v6
	v_sub_f32_e32 v4, v10, v7
	v_mul_f32_e32 v13, v5, v11
	v_sub_f32_e32 v12, v8, v6
	v_mul_f32_e32 v6, v10, v13
	v_sub_f32_e32 v3, v3, v4
	v_fma_f32 v8, v13, v10, -v6
	v_fmac_f32_e32 v8, v13, v3
	v_add_f32_e32 v4, v6, v8
	v_sub_f32_e32 v7, v5, v4
	v_mov_b32_e32 v9, v4
	v_pk_add_f32 v[4:5], v[4:5], v[6:7] neg_lo:[0,1] neg_hi:[0,1]
	v_cvt_f32_i32_e32 v2, v2
	v_pk_add_f32 v[4:5], v[4:5], v[8:9] neg_lo:[0,1] neg_hi:[0,1]
	s_addc_u32 s55, s30, 0
	v_add_f32_e32 v5, v12, v5
	v_add_f32_e32 v4, v4, v5
	v_add_f32_e32 v5, v7, v4
	v_mul_f32_e32 v9, v11, v5
	v_mul_f32_e32 v6, v10, v9
	v_sub_f32_e32 v7, v7, v5
	v_add_f32_e32 v14, v13, v9
	v_fma_f32 v8, v9, v10, -v6
	v_add_f32_e32 v12, v4, v7
	v_sub_f32_e32 v4, v14, v13
	v_fmac_f32_e32 v8, v9, v3
	v_sub_f32_e32 v3, v9, v4
	v_add_f32_e32 v4, v6, v8
	v_sub_f32_e32 v7, v5, v4
	v_mov_b32_e32 v9, v4
	v_pk_add_f32 v[4:5], v[4:5], v[6:7] neg_lo:[0,1] neg_hi:[0,1]
	s_ashr_i32 s36, s53, 7
	v_pk_add_f32 v[4:5], v[4:5], v[8:9] neg_lo:[0,1] neg_hi:[0,1]
	s_cmp_eq_u32 s4, 0
	v_add_f32_e32 v5, v12, v5
	v_add_f32_e32 v4, v4, v5
	v_add_f32_e32 v4, v7, v4
	v_mul_f32_e32 v4, v11, v4
	v_add_f32_e32 v3, v3, v4
	v_add_f32_e32 v4, v14, v3
	v_mul_f32_e32 v6, v4, v4
	v_sub_f32_e32 v7, v4, v14
	v_fmamk_f32 v8, v6, 0x3e9b6dac, v213
	v_sub_f32_e32 v7, v3, v7
	v_mul_f32_e32 v3, v4, v6
	v_fmaak_f32 v185, v6, v8, 0x3f2aaada
	v_ldexp_f32 v9, v7, 1
	v_pk_mul_f32 v[6:7], v[2:3], v[184:185]
	s_mov_b32 s4, 0x3f317218
	v_ldexp_f32 v5, v4, 1
	v_fma_f32 v4, v2, s4, -v6
	v_fmac_f32_e32 v4, 0xb102e308, v2
	v_pk_add_f32 v[2:3], v[6:7], v[4:5]
	v_mov_b32_e32 v8, v6
	v_sub_f32_e32 v12, v3, v5
	v_pk_add_f32 v[10:11], v[2:3], v[6:7] neg_lo:[0,1] neg_hi:[0,1]
	v_sub_f32_e32 v7, v7, v12
	v_add_f32_e32 v9, v9, v7
	v_pk_add_f32 v[14:15], v[2:3], v[8:9]
	v_mov_b32_e32 v5, v2
	v_mov_b32_e32 v11, v15
	v_pk_add_f32 v[20:21], v[4:5], v[10:11] neg_lo:[0,1] neg_hi:[0,1]
	v_pk_add_f32 v[4:5], v[4:5], v[10:11]
	v_mov_b32_e32 v6, v3
	v_mov_b32_e32 v13, v2
	v_pk_add_f32 v[2:3], v[4:5], v[2:3] op_sel:[1,0] op_sel_hi:[0,1] neg_lo:[0,1] neg_hi:[0,1]
	v_mov_b32_e32 v12, v9
	v_mov_b32_e32 v8, v15
	v_mov_b32_e32 v9, v5
	v_mov_b32_e32 v7, v2
	v_pk_add_f32 v[10:11], v[14:15], v[2:3] op_sel_hi:[1,0] neg_lo:[0,1] neg_hi:[0,1]
	v_pk_add_f32 v[2:3], v[8:9], v[6:7] neg_lo:[0,1] neg_hi:[0,1]
	v_mov_b32_e32 v10, v20
	v_pk_add_f32 v[2:3], v[12:13], v[2:3] neg_lo:[0,1] neg_hi:[0,1]
	v_mov_b32_e32 v21, v5
	v_pk_add_f32 v[6:7], v[10:11], v[2:3]
	v_cmp_nlt_f32_e32 vcc, 1.0, v16
	v_pk_add_f32 v[8:9], v[6:7], v[6:7] op_sel:[0,1] op_sel_hi:[1,0]
	s_mov_b32 s4, 0x33800000
	v_pk_add_f32 v[4:5], v[4:5], v[8:9] op_sel:[1,0] op_sel_hi:[0,1]
	v_mov_b32_e32 v7, v4
	v_mov_b32_e32 v3, v8
	v_pk_add_f32 v[8:9], v[6:7], v[20:21] neg_lo:[0,1] neg_hi:[0,1]
	v_cmp_lt_f32_e64 s[4:5], |v16|, s4
	v_sub_f32_e32 v5, v6, v8
	v_pk_add_f32 v[2:3], v[2:3], v[8:9] neg_lo:[0,1] neg_hi:[0,1]
	v_sub_f32_e32 v5, v20, v5
	v_add_f32_e32 v2, v2, v5
; __device__ __forceinline__ float ret_log_gamma(const float* dexp, int dir, int h) { return log1pf(-exp2f(-dexp[dir * 8 + h])); }
; __device__ __forceinline__ void ret_scan(const bf16* proj, bf16* ST, bf16* FS, const float* dexp, LAS unsigned char* lds, int vb, int nb, int tid_in, int wave) {
;     ...
;         const float lg = ret_log_gamma(dexp, dir, h), gC = expf(128.0f * lg);
;         f32x4 acc[8][2];
; #pragma unroll
;         for (int m = 0; m < 8; ++m) { acc[m][0] = (f32x4){0.f, 0.f, 0.f, 0.f}; acc[m][1] = (f32x4){0.f, 0.f, 0.f, 0.f}; }
;         v4u kr[4], vr[8];
;         { const int n0 = dir == 0 ? 0 : N - 1, rowb = base + n0 * 128;
; #pragma unroll
;           for (int i = 0; i < 4; ++i) { const int id = tid + 512 * i, j = id >> 4, ch = id & 15; kr[i] = *(const v4u*)(proj + (size_t)(rowb + j) * NIN + C_RK + h * 256 + dsl * 128 + ch * 8); }
; #pragma unroll
;           for (int i = 0; i < 8; ++i) { const int id = tid + 512 * i, j = id >> 5, ch = id & 31; vr[i] = *(const v4u*)(proj + (size_t)(rowb + j) * NIN + C_RV + h * 256 + ch * 8); } }
;         v2u stq[8][2]; bf16* dst_prev = nullptr;
;         for (int step = 0; step <= nsteps; ++step) {
;             const int n = dir == 0 ? step : N - 1 - step, tgt = dir == 0 ? n + 1 : n - 1;
;             if (step < nsteps) {
;                 __syncthreads();
	v_add_f32_e32 v2, v2, v3
	v_add_f32_e32 v2, v4, v2
	v_cndmask_b32_e32 v2, v220, v2, vcc
	v_cmp_neq_f32_e32 vcc, 1.0, v16
	s_movk_i32 s30, 0x700
	v_lshlrev_b32_e32 v14, 1, v114
	v_cndmask_b32_e32 v2, v221, v2, vcc
	v_cndmask_b32_e64 v20, v2, -v16, s[4:5]
	v_mul_f32_e32 v2, 0x43000000, v20
	v_mul_f32_e32 v3, 0x3fb8aa3b, v2
	v_fma_f32 v4, v2, s96, -v3
	v_rndne_f32_e32 v5, v3
	v_fmac_f32_e32 v4, 0x32a5705f, v2
	v_sub_f32_e32 v3, v3, v5
	v_add_f32_e32 v3, v3, v4
	v_exp_f32_e32 v3, v3
	v_cvt_i32_f32_e32 v4, v5
	v_cmp_ngt_f32_e32 vcc, s97, v2
	s_cselect_b64 s[4:5], -1, 0
	s_and_b64 s[50:51], s[4:5], exec
	v_ldexp_f32 v3, v3, v4
	v_cndmask_b32_e32 v3, 0, v3, vcc
	v_cmp_nlt_f32_e32 vcc, s12, v2
	v_sub_u32_e32 v2, 0x7f, v1
	v_cndmask_b32_e64 v21, v1, v2, s[4:5]
	s_cselect_b32 s56, 1, -1
	v_lshlrev_b32_e32 v2, 1, v102
	v_and_b32_e32 v66, 28, v2
	v_lshlrev_b32_e32 v2, 4, v102
	s_cselect_b32 s30, 0x80, s30
	s_add_i32 s56, s56, s36
	v_and_b32_e32 v2, 16, v2
	s_add_u32 s57, s26, s31
	v_add_u32_e32 v16, 0, v2
	v_lshlrev_b32_e32 v2, 6, v102
	s_addc_u32 s58, s27, 0
	s_and_b32 s31, s42, 0x780
	v_cndmask_b32_e32 v148, v222, v3, vcc
	v_and_b32_e32 v2, 0x780, v2
	v_and_b32_e32 v3, 0x60, v102
	s_or_b32 s31, s31, s53
	v_add3_u32 v67, v16, v2, v3
	v_add_u32_e32 v2, s31, v181
	v_mad_i64_i32 v[2:3], s[36:37], v2, s33, v[42:43]
	s_lshl_b32 s62, s47, 9
	v_lshl_add_u64 v[2:3], v[2:3], 0, s[62:63]
	v_add_u32_e32 v4, s31, v180
	v_lshl_add_u64 v[2:3], v[2:3], 0, v[182:183]
	v_mad_i64_i32 v[4:5], s[36:37], v4, s33, v[42:43]
	v_add_co_u32_e32 v2, vcc, s40, v2
	v_lshl_add_u64 v[4:5], v[4:5], 0, s[62:63]
	v_add_u32_e32 v10, s31, v179
	v_addc_co_u32_e32 v3, vcc, 0, v3, vcc
	v_lshl_add_u64 v[4:5], v[4:5], 0, v[182:183]
	v_mad_i64_i32 v[10:11], s[36:37], v10, s33, v[42:43]
	v_add_u32_e32 v12, s31, v147
	v_add_co_u32_e32 v6, vcc, s40, v4
	v_lshl_add_u64 v[10:11], v[10:11], 0, s[62:63]
	v_mad_i64_i32 v[12:13], s[50:51], v12, s33, v[42:43]
	v_addc_co_u32_e32 v7, vcc, 0, v5, vcc
	v_lshl_add_u64 v[10:11], v[10:11], 0, v[182:183]
	s_lshl_b32 s36, s64, 1
	s_mov_b32 s37, s63
	v_lshl_add_u64 v[12:13], v[12:13], 0, s[62:63]
	v_add_u32_e32 v22, s31, v1
	v_add_co_u32_e32 v10, vcc, s40, v10
	v_mov_b32_e32 v15, v183
	v_lshl_add_u64 v[12:13], v[12:13], 0, s[36:37]
	v_mad_i64_i32 v[22:23], s[50:51], v22, s33, v[42:43]
	v_addc_co_u32_e32 v11, vcc, 0, v11, vcc
	v_lshl_add_u64 v[12:13], v[12:13], 0, v[14:15]
	v_lshl_add_u64 v[22:23], v[22:23], 0, s[62:63]
	v_add_co_u32_e32 v12, vcc, s49, v12
	v_lshl_add_u64 v[22:23], v[22:23], 0, s[36:37]
	s_nop 0
	v_addc_co_u32_e32 v13, vcc, 0, v13, vcc
	v_lshl_add_u64 v[22:23], v[22:23], 0, v[14:15]
	v_add_co_u32_e32 v26, vcc, s49, v22
	global_load_dwordx4 v[2:5], v[2:3], off
	s_nop 0
	global_load_dwordx4 v[6:9], v[6:7], off
	v_addc_co_u32_e32 v27, vcc, 0, v23, vcc
	global_load_dwordx4 v[22:25], v[12:13], off
	s_nop 0
	global_load_dwordx4 v[26:29], v[26:27], off
	v_add_u32_e32 v30, s31, v178
	v_mad_i64_i32 v[12:13], s[50:51], v30, s33, v[42:43]
	v_lshl_add_u64 v[12:13], v[12:13], 0, s[62:63]
	v_add_u32_e32 v34, s31, v177
	v_add_u32_e32 v44, s31, v175
	v_lshl_add_u64 v[12:13], v[12:13], 0, v[182:183]
	v_mad_i64_i32 v[34:35], s[50:51], v34, s33, v[42:43]
	v_mad_i64_i32 v[44:45], s[50:51], v44, s33, v[42:43]
	v_add_co_u32_e32 v30, vcc, s40, v12
	v_lshl_add_u64 v[34:35], v[34:35], 0, s[62:63]
	v_add_u32_e32 v36, s31, v176
	v_lshl_add_u64 v[44:45], v[44:45], 0, s[62:63]
	v_addc_co_u32_e32 v31, vcc, 0, v13, vcc
	v_lshl_add_u64 v[34:35], v[34:35], 0, v[182:183]
	v_mad_i64_i32 v[36:37], s[50:51], v36, s33, v[42:43]
	v_lshl_add_u64 v[52:53], v[44:45], 0, v[182:183]
	v_add_u32_e32 v44, s31, v173
	v_add_co_u32_e32 v34, vcc, s40, v34
	v_lshl_add_u64 v[36:37], v[36:37], 0, s[62:63]
	v_mad_i64_i32 v[44:45], s[50:51], v44, s33, v[42:43]
	v_addc_co_u32_e32 v35, vcc, 0, v35, vcc
	v_lshl_add_u64 v[36:37], v[36:37], 0, v[182:183]
	v_lshl_add_u64 v[44:45], v[44:45], 0, s[62:63]
	v_add_u32_e32 v46, s31, v172
	v_add_co_u32_e32 v38, vcc, s40, v36
	v_lshl_add_u64 v[44:45], v[44:45], 0, s[36:37]
	v_mad_i64_i32 v[46:47], s[50:51], v46, s33, v[42:43]
	v_addc_co_u32_e32 v39, vcc, 0, v37, vcc
	v_lshl_add_u64 v[44:45], v[44:45], 0, v[14:15]
	v_lshl_add_u64 v[46:47], v[46:47], 0, s[62:63]
	v_add_co_u32_e32 v44, vcc, s49, v44
	v_lshl_add_u64 v[46:47], v[46:47], 0, s[36:37]
	s_nop 0
	v_addc_co_u32_e32 v45, vcc, 0, v45, vcc
	v_lshl_add_u64 v[46:47], v[46:47], 0, v[14:15]
	v_add_co_u32_e32 v48, vcc, s49, v46
	global_load_dwordx4 v[10:13], v[10:11], off
	s_nop 0
	global_load_dwordx4 v[30:33], v[30:31], off
	v_addc_co_u32_e32 v49, vcc, 0, v47, vcc
	global_load_dwordx4 v[34:37], v[34:35], off
	s_nop 0
	global_load_dwordx4 v[38:41], v[38:39], off
	s_nop 0
	global_load_dwordx4 v[44:47], v[44:45], off
	s_nop 0
	global_load_dwordx4 v[48:51], v[48:49], off
	v_cvt_f32_i32_e32 v21, v21
	v_add_u32_e32 v54, s31, v174
	v_mad_i64_i32 v[54:55], s[50:51], v54, s33, v[42:43]
	v_add_co_u32_e32 v52, vcc, s40, v52
	v_lshl_add_u64 v[54:55], v[54:55], 0, s[62:63]
	s_nop 0
	v_addc_co_u32_e32 v53, vcc, 0, v53, vcc
	v_lshl_add_u64 v[54:55], v[54:55], 0, v[182:183]
	v_mul_f32_e32 v21, v20, v21
	v_add_co_u32_e32 v56, vcc, s40, v54
	v_mul_f32_e32 v21, 0x3fb8aa3b, v21
	s_nop 0
	v_addc_co_u32_e32 v57, vcc, 0, v55, vcc
	v_exp_f32_e32 v150, v21
	global_load_dwordx4 v[52:55], v[52:53], off
	s_nop 0
	global_load_dwordx4 v[56:59], v[56:57], off
	v_lshrrev_b32_e32 v21, 6, v102
	v_mov_b32_e32 v151, v150
	s_barrier
; #define LAS __attribute__((address_space(3)))
; __device__ __forceinline__ unsigned pk2(float lo, float hi) { const f32x2 v = {lo, hi}; return __builtin_bit_cast(unsigned, __builtin_convertvector(v, bf16x2_t)); }
; __device__ __forceinline__ int trw_off(int row, int c8  , int GP) { return (row >> 2) * GP + (((c8 >> 1) * 4 + (row & 3)) * 32) + (c8 & 1) * 16; }
; __device__ __forceinline__ void ret_scan(const bf16* proj, bf16* ST, bf16* FS, const float* dexp, LAS unsigned char* lds, int vb, int nb, int tid_in, int wave) {
;     ...
; #pragma unroll
;                 for (int i = 0; i < 4; ++i) { const int id = tid + 512 * i, j = id >> 4, ch = id & 15;
;                     v4u val = kr[i];
;                     const float z = __expf(lg * (float)(dir == 0 ? 127 - j : j));
;                     val.x = pk2(bflo(val.x) * z, bfhi(val.x) * z); val.y = pk2(bflo(val.y) * z, bfhi(val.y) * z); val.z = pk2(bflo(val.z) * z, bfhi(val.z) * z); val.w = pk2(bflo(val.w) * z, bfhi(val.w) * z);
;                     *(LAS v4u*)(Kt + trw_off(j, ch, 1088)) = val; }
; #pragma unroll
;                 for (int i = 0; i < 8; ++i) { const int id = tid + 512 * i, j = id >> 5, ch = id & 31; *(LAS v4u*)(Vt + trw_off(j, ch, 2112)) = vr[i]; }
;                 __syncthreads();
	s_movk_i32 s31, 0x1080
	s_waitcnt vmcnt(8)
	v_lshlrev_b32_e32 v60, 16, v26
	v_and_b32_e32 v61, 0xffff0000, v26
	v_pk_mul_f32 v[60:61], v[150:151], v[60:61] op_sel_hi:[0,1]
	v_cvt_pk_bf16_f32 v26, v60, v61
	v_lshlrev_b32_e32 v60, 16, v27
	v_and_b32_e32 v61, 0xffff0000, v27
	v_pk_mul_f32 v[60:61], v[150:151], v[60:61] op_sel_hi:[0,1]
	v_cvt_pk_bf16_f32 v27, v60, v61
	v_lshlrev_b32_e32 v60, 16, v28
	v_and_b32_e32 v61, 0xffff0000, v28
	v_pk_mul_f32 v[60:61], v[150:151], v[60:61] op_sel_hi:[0,1]
	v_cvt_pk_bf16_f32 v28, v60, v61
	v_lshlrev_b32_e32 v60, 16, v29
	v_and_b32_e32 v61, 0xffff0000, v29
	v_pk_mul_f32 v[60:61], v[150:151], v[60:61] op_sel_hi:[0,1]
	v_cvt_pk_bf16_f32 v29, v60, v61
	v_and_or_b32 v60, v1, 3, v66
	v_lshlrev_b32_e32 v68, 5, v60
	v_sub_u32_e32 v60, 0x7f, v147
	v_cndmask_b32_e64 v60, v147, v60, s[4:5]
	v_cvt_f32_i32_e32 v69, v60
	v_mad_u64_u32 v[60:61], s[50:51], v21, s59, v[16:17]
	v_add_u32_e32 v185, v60, v68
	v_mul_f32_e32 v21, v20, v69
	v_mul_f32_e32 v21, 0x3fb8aa3b, v21
	v_exp_f32_e32 v152, v21
	ds_write_b128 v185, v[26:29]
	v_lshlrev_b32_e32 v26, 16, v22
	v_and_b32_e32 v27, 0xffff0000, v22
	v_mov_b32_e32 v153, v152
	v_pk_mul_f32 v[26:27], v[152:153], v[26:27] op_sel_hi:[0,1]
	v_cvt_pk_bf16_f32 v22, v26, v27
	v_lshlrev_b32_e32 v26, 16, v23
	v_and_b32_e32 v27, 0xffff0000, v23
	v_pk_mul_f32 v[26:27], v[152:153], v[26:27] op_sel_hi:[0,1]
	v_cvt_pk_bf16_f32 v23, v26, v27
	v_lshlrev_b32_e32 v26, 16, v24
	v_and_b32_e32 v27, 0xffff0000, v24
	v_pk_mul_f32 v[26:27], v[152:153], v[26:27] op_sel_hi:[0,1]
	v_cvt_pk_bf16_f32 v24, v26, v27
	v_lshlrev_b32_e32 v26, 16, v25
	v_and_b32_e32 v27, 0xffff0000, v25
	v_pk_mul_f32 v[26:27], v[152:153], v[26:27] op_sel_hi:[0,1]
	v_cvt_pk_bf16_f32 v25, v26, v27
	v_and_or_b32 v26, v147, 3, v66
	v_lshlrev_b32_e32 v28, 5, v26
	v_sub_u32_e32 v26, 0x7f, v172
	v_cndmask_b32_e64 v26, v172, v26, s[4:5]
	v_cvt_f32_i32_e32 v29, v26
	v_lshrrev_b32_e32 v21, 6, v19
	v_mad_u64_u32 v[26:27], s[50:51], v21, s59, v[16:17]
	v_mul_f32_e32 v21, v20, v29
	v_mul_f32_e32 v21, 0x3fb8aa3b, v21
	v_exp_f32_e32 v154, v21
	v_add_u32_e32 v186, v26, v28
	ds_write_b128 v186, v[22:25]
	s_waitcnt vmcnt(2)
	v_lshlrev_b32_e32 v22, 16, v48
	v_and_b32_e32 v23, 0xffff0000, v48
	v_mov_b32_e32 v155, v154
	v_lshlrev_b32_e32 v24, 16, v49
	v_and_b32_e32 v25, 0xffff0000, v49
	v_pk_mul_f32 v[22:23], v[154:155], v[22:23] op_sel_hi:[0,1]
	v_pk_mul_f32 v[24:25], v[154:155], v[24:25] op_sel_hi:[0,1]
	v_cvt_pk_bf16_f32 v22, v22, v23
	v_cvt_pk_bf16_f32 v23, v24, v25
	v_lshlrev_b32_e32 v24, 16, v50
	v_and_b32_e32 v25, 0xffff0000, v50
	v_lshlrev_b32_e32 v26, 16, v51
	v_and_b32_e32 v27, 0xffff0000, v51
	v_pk_mul_f32 v[24:25], v[154:155], v[24:25] op_sel_hi:[0,1]
	v_pk_mul_f32 v[26:27], v[154:155], v[26:27] op_sel_hi:[0,1]
	v_cvt_pk_bf16_f32 v24, v24, v25
	v_cvt_pk_bf16_f32 v25, v26, v27
	v_and_or_b32 v26, v172, 3, v66
	v_lshlrev_b32_e32 v28, 5, v26
	v_sub_u32_e32 v26, 0x7f, v173
	v_cndmask_b32_e64 v26, v173, v26, s[4:5]
	v_cvt_f32_i32_e32 v29, v26
	v_lshrrev_b32_e32 v21, 6, v18
	v_mad_u64_u32 v[26:27], s[50:51], v21, s59, v[16:17]
	v_mul_f32_e32 v20, v20, v29
	v_mul_f32_e32 v20, 0x3fb8aa3b, v20
	v_exp_f32_e32 v156, v20
	v_add_u32_e32 v189, v26, v28
	ds_write_b128 v189, v[22:25]
	v_lshlrev_b32_e32 v20, 16, v44
	v_and_b32_e32 v21, 0xffff0000, v44
	v_mov_b32_e32 v157, v156
	v_lshlrev_b32_e32 v22, 16, v45
	v_and_b32_e32 v23, 0xffff0000, v45
	v_pk_mul_f32 v[20:21], v[156:157], v[20:21] op_sel_hi:[0,1]
	v_pk_mul_f32 v[22:23], v[156:157], v[22:23] op_sel_hi:[0,1]
	v_cvt_pk_bf16_f32 v20, v20, v21
	v_cvt_pk_bf16_f32 v21, v22, v23
	v_lshlrev_b32_e32 v22, 16, v46
	v_and_b32_e32 v23, 0xffff0000, v46
	v_lshlrev_b32_e32 v24, 16, v47
	v_and_b32_e32 v25, 0xffff0000, v47
	v_pk_mul_f32 v[22:23], v[156:157], v[22:23] op_sel_hi:[0,1]
	v_pk_mul_f32 v[24:25], v[156:157], v[24:25] op_sel_hi:[0,1]
	v_cvt_pk_bf16_f32 v22, v22, v23
	v_cvt_pk_bf16_f32 v23, v24, v25
	v_lshrrev_b32_e32 v24, 6, v17
	v_and_or_b32 v25, v173, 3, v66
	v_lshlrev_b32_e32 v26, 5, v25
	v_mad_u64_u32 v[24:25], s[50:51], v24, s59, v[16:17]
	v_ashrrev_i32_e32 v16, 7, v102
	v_mul_lo_u32 v16, v16, s73
	v_add_u32_e32 v192, v67, v16
	v_ashrrev_i32_e32 v16, 7, v19
	v_mul_lo_u32 v16, v16, s73
	v_add_u32_e32 v198, v67, v16
	v_ashrrev_i32_e32 v16, 7, v18
	v_mul_lo_u32 v16, v16, s73
	v_add_u32_e32 v199, v67, v16
	v_ashrrev_i32_e32 v16, 7, v17
	v_mul_lo_u32 v16, v16, s73
	v_add_u32_e32 v200, v67, v16
	v_ashrrev_i32_e32 v16, 7, v62
	v_mul_lo_u32 v16, v16, s73
	v_add_u32_e32 v201, v67, v16
	v_ashrrev_i32_e32 v16, 7, v63
	v_mul_lo_u32 v16, v16, s73
	v_add_u32_e32 v190, v24, v26
	v_add_u32_e32 v202, v67, v16
	ds_write_b128 v190, v[20:23]
	s_waitcnt vmcnt(0)
	ds_write_b128 v192, v[56:59] offset:34816
	ds_write_b128 v198, v[52:55] offset:34816
	ds_write_b128 v199, v[38:41] offset:34816
	ds_write_b128 v200, v[34:37] offset:34816
	ds_write_b128 v201, v[30:33] offset:34816
	ds_write_b128 v202, v[10:13] offset:34816
	v_ashrrev_i32_e32 v10, 7, v64
	v_mul_lo_u32 v10, v10, s73
	v_add_u32_e32 v203, v67, v10
	ds_write_b128 v203, v[6:9] offset:34816
	v_ashrrev_i32_e32 v6, 7, v65
	v_mul_lo_u32 v6, v6, s73
	v_add_u32_e32 v204, v67, v6
	v_mad_u32_u24 v16, v110, s31, v115
	v_mad_u32_u24 v40, v110, s77, v117
	ds_write_b128 v204, v[2:5] offset:34816
	s_waitcnt lgkmcnt(0)
	s_barrier
; #define LAS __attribute__((address_space(3)))
; __device__ __forceinline__ s16x4 tr16(const LAS unsigned char* p) { return __builtin_bit_cast(s16x4, __builtin_amdgcn_ds_read_tr16_b64_v4i16((LAS s16x4*)p)); }
; __device__ __forceinline__ bf16x8 cat8(s16x4 lo, s16x4 hi) { return __builtin_shufflevector(lo, hi, 0, 1, 2, 3, 4, 5, 6, 7); }
; __device__ __forceinline__ f32x4 mfma16(bf16x8 a, bf16x8 b, f32x4 c) { return __builtin_amdgcn_mfma_f32_16x16x32_bf16(a, b, c, 0, 0, 0); }
; __device__ __forceinline__ void ret_scan(const bf16* proj, bf16* ST, bf16* FS, const float* dexp, LAS unsigned char* lds, int vb, int nb, int tid_in, int wave) {
;     ...
;             for (int m = 0; m < 8; ++m) { acc[m][0] = acc[m][0] * gC; acc[m][1] = acc[m][1] * gC; }
; #pragma unroll
;             for (int ks = 0; ks < 4; ++ks) {
;                 const int rho = 8 * ks + 2 * g, lo8 = (qi >> 2) * 32 + (qi & 3) * 8;
;                 bf16x8 bfr[2];
; #pragma unroll
;                 for (int nt = 0; nt < 2; ++nt) { const LAS unsigned char* p = Vt + rho * 2112 + (2 * wave + nt) * 128 + lo8; bfr[nt] = cat8(tr16(p), tr16(p + 2112)); }
; #pragma unroll
;                 for (int m = 0; m < 8; ++m) { const LAS unsigned char* p = Kt + rho * 1088 + m * 128 + lo8; const bf16x8 af = cat8(tr16(p), tr16(p + 1088));
;                     acc[m][0] = mfma16(af, bfr[0], acc[m][0]); acc[m][1] = mfma16(af, bfr[1], acc[m][1]); }
;             }
	v_mul_f32_e32 v2, 0, v148
	ds_read_b64_tr_b16 v[6:7], v40
	ds_read_b64_tr_b16 v[8:9], v40 offset:1088
	ds_read_b64_tr_b16 v[10:11], v16 offset:34816
	ds_read_b64_tr_b16 v[12:13], v16 offset:36928
	ds_read_b64_tr_b16 v[18:19], v16 offset:37056
	ds_read_b64_tr_b16 v[16:17], v16 offset:34944
	ds_read_b64_tr_b16 v[20:21], v40 offset:128
	ds_read_b64_tr_b16 v[24:25], v40 offset:256
	ds_read_b64_tr_b16 v[28:29], v40 offset:384
	ds_read_b64_tr_b16 v[22:23], v40 offset:1216
	ds_read_b64_tr_b16 v[26:27], v40 offset:1344
	ds_read_b64_tr_b16 v[30:31], v40 offset:1472
	ds_read_b64_tr_b16 v[52:53], v40 offset:512
	ds_read_b64_tr_b16 v[54:55], v40 offset:1600
	ds_read_b64_tr_b16 v[56:57], v40 offset:640
	ds_read_b64_tr_b16 v[60:61], v40 offset:768
	ds_read_b64_tr_b16 v[64:65], v40 offset:896
	ds_read_b64_tr_b16 v[58:59], v40 offset:1728
	ds_read_b64_tr_b16 v[62:63], v40 offset:1856
	ds_read_b64_tr_b16 v[66:67], v40 offset:1984
	v_mov_b32_e32 v3, v2
	v_mov_b32_e32 v4, v2
	v_mov_b32_e32 v5, v2
	v_mad_u32_u24 v40, v111, s73, v115
	s_or_b32 s30, s30, s53
	s_waitcnt lgkmcnt(14)
	v_mfma_f32_16x16x32_bf16 v[32:35], v[6:9], v[10:13], v[2:5]
	s_mov_b32 s59, 1
	v_mov_b32_e32 v158, v148
	v_mov_b32_e32 v159, v148
	v_mfma_f32_16x16x32_bf16 v[6:9], v[6:9], v[16:19], v[2:5]
	s_waitcnt lgkmcnt(10)
	v_mfma_f32_16x16x32_bf16 v[36:39], v[20:23], v[10:13], v[2:5]
	v_mfma_f32_16x16x32_bf16 v[20:23], v[20:23], v[16:19], v[2:5]
	s_waitcnt lgkmcnt(9)
	v_mfma_f32_16x16x32_bf16 v[44:47], v[24:27], v[10:13], v[2:5]
	v_mfma_f32_16x16x32_bf16 v[24:27], v[24:27], v[16:19], v[2:5]
	s_waitcnt lgkmcnt(8)
	v_mfma_f32_16x16x32_bf16 v[48:51], v[28:31], v[10:13], v[2:5]
	v_mfma_f32_16x16x32_bf16 v[28:31], v[28:31], v[16:19], v[2:5]
	s_waitcnt lgkmcnt(6)
	v_mfma_f32_16x16x32_bf16 v[68:71], v[52:55], v[10:13], v[2:5]
	v_mfma_f32_16x16x32_bf16 v[52:55], v[52:55], v[16:19], v[2:5]
	s_waitcnt lgkmcnt(2)
	v_mfma_f32_16x16x32_bf16 v[72:75], v[56:59], v[10:13], v[2:5]
	v_mfma_f32_16x16x32_bf16 v[56:59], v[56:59], v[16:19], v[2:5]
	s_waitcnt lgkmcnt(1)
	v_mfma_f32_16x16x32_bf16 v[76:79], v[60:63], v[10:13], v[2:5]
	v_mfma_f32_16x16x32_bf16 v[60:63], v[60:63], v[16:19], v[2:5]
	s_waitcnt lgkmcnt(0)
	v_mfma_f32_16x16x32_bf16 v[10:13], v[64:67], v[10:13], v[2:5]
	v_mfma_f32_16x16x32_bf16 v[16:19], v[64:67], v[16:19], v[2:5]
	s_nop 2
	ds_read_b64_tr_b16 v[2:3], v103
	ds_read_b64_tr_b16 v[4:5], v103 offset:1088
	ds_read_b64_tr_b16 v[64:65], v40 offset:34816
	ds_read_b64_tr_b16 v[66:67], v40 offset:36928
	ds_read_b64_tr_b16 v[82:83], v40 offset:37056
	ds_read_b64_tr_b16 v[80:81], v40 offset:34944
	ds_read_b64_tr_b16 v[84:85], v103 offset:128
	ds_read_b64_tr_b16 v[88:89], v103 offset:256
	ds_read_b64_tr_b16 v[92:93], v103 offset:384
	ds_read_b64_tr_b16 v[86:87], v103 offset:1216
	ds_read_b64_tr_b16 v[90:91], v103 offset:1344
	ds_read_b64_tr_b16 v[94:95], v103 offset:1472
	v_add_u32_e32 v40, s30, v172
	v_mad_i64_i32 v[40:41], s[50:51], v40, s33, v[42:43]
	s_waitcnt lgkmcnt(8)
	v_mfma_f32_16x16x32_bf16 v[32:35], v[2:5], v[64:67], v[32:35]
	v_lshl_add_u64 v[40:41], v[40:41], 0, s[62:63]
	v_lshl_add_u64 v[40:41], v[40:41], 0, s[36:37]
	v_lshl_add_u64 v[40:41], v[40:41], 0, v[14:15]
	s_waitcnt lgkmcnt(6)
	v_mfma_f32_16x16x32_bf16 v[96:99], v[2:5], v[80:83], v[6:9]
	v_add_u32_e32 v2, s30, v1
	v_mad_i64_i32 v[2:3], s[50:51], v2, s33, v[42:43]
	v_lshl_add_u64 v[2:3], v[2:3], 0, s[62:63]
	v_lshl_add_u64 v[2:3], v[2:3], 0, s[36:37]
	v_lshl_add_u64 v[6:7], v[2:3], 0, v[14:15]
	ds_read_b64_tr_b16 v[2:3], v103 offset:512
	ds_read_b64_tr_b16 v[4:5], v103 offset:1600
	s_waitcnt lgkmcnt(4)
	v_mfma_f32_16x16x32_bf16 v[36:39], v[84:87], v[64:67], v[36:39]
	v_add_u32_e32 v8, s30, v147
	v_mad_i64_i32 v[8:9], s[50:51], v8, s33, v[42:43]
	v_mfma_f32_16x16x32_bf16 v[20:23], v[84:87], v[80:83], v[20:23]
	v_add_co_u32_e32 v6, vcc, s49, v6
	s_waitcnt lgkmcnt(3)
	v_mfma_f32_16x16x32_bf16 v[44:47], v[88:91], v[64:67], v[44:47]
	v_addc_co_u32_e32 v7, vcc, 0, v7, vcc
	v_mfma_f32_16x16x32_bf16 v[24:27], v[88:91], v[80:83], v[24:27]
	s_waitcnt lgkmcnt(2)
	v_mfma_f32_16x16x32_bf16 v[48:51], v[92:95], v[64:67], v[48:51]
	v_mfma_f32_16x16x32_bf16 v[28:31], v[92:95], v[80:83], v[28:31]
	ds_read_b64_tr_b16 v[84:85], v103 offset:640
	ds_read_b64_tr_b16 v[88:89], v103 offset:768
	ds_read_b64_tr_b16 v[92:93], v103 offset:896
	ds_read_b64_tr_b16 v[86:87], v103 offset:1728
	ds_read_b64_tr_b16 v[90:91], v103 offset:1856
	ds_read_b64_tr_b16 v[94:95], v103 offset:1984
	s_waitcnt lgkmcnt(6)
	v_mfma_f32_16x16x32_bf16 v[68:71], v[2:5], v[64:67], v[68:71]
	v_mfma_f32_16x16x32_bf16 v[52:55], v[2:5], v[80:83], v[52:55]
	v_lshl_add_u64 v[2:3], v[8:9], 0, s[62:63]
	v_lshl_add_u64 v[2:3], v[2:3], 0, s[36:37]
	v_lshl_add_u64 v[2:3], v[2:3], 0, v[14:15]
	s_waitcnt lgkmcnt(2)
	v_mfma_f32_16x16x32_bf16 v[72:75], v[84:87], v[64:67], v[72:75]
	v_add_co_u32_e32 v8, vcc, s49, v2
	s_waitcnt lgkmcnt(1)
	v_mfma_f32_16x16x32_bf16 v[76:79], v[88:91], v[64:67], v[76:79]
	v_addc_co_u32_e32 v9, vcc, 0, v3, vcc
	v_add_co_u32_e32 v40, vcc, s49, v40
	s_waitcnt lgkmcnt(0)
; #define LAS __attribute__((address_space(3)))
; __device__ __forceinline__ s16x4 tr16(const LAS unsigned char* p) { return __builtin_bit_cast(s16x4, __builtin_amdgcn_ds_read_tr16_b64_v4i16((LAS s16x4*)p)); }
; __device__ __forceinline__ bf16x8 cat8(s16x4 lo, s16x4 hi) { return __builtin_shufflevector(lo, hi, 0, 1, 2, 3, 4, 5, 6, 7); }
; __device__ __forceinline__ f32x4 mfma16(bf16x8 a, bf16x8 b, f32x4 c) { return __builtin_amdgcn_mfma_f32_16x16x32_bf16(a, b, c, 0, 0, 0); }
; __device__ __forceinline__ void ret_scan(const bf16* proj, bf16* ST, bf16* FS, const float* dexp, LAS unsigned char* lds, int vb, int nb, int tid_in, int wave) {
;     ...
;             if (step + 1 < nsteps) { const int n1 = dir == 0 ? step + 1 : N - 2 - step, rowb = base + n1 * 128;
; #pragma unroll
;                 for (int i = 0; i < 4; ++i) { const int id = tid + 512 * i, j = id >> 4, ch = id & 15; kr[i] = *(const v4u*)(proj + (size_t)(rowb + j) * NIN + C_RK + h * 256 + dsl * 128 + ch * 8); }
; #pragma unroll
;                 for (int i = 0; i < 8; ++i) { const int id = tid + 512 * i, j = id >> 5, ch = id & 31; vr[i] = *(const v4u*)(proj + (size_t)(rowb + j) * NIN + C_RV + h * 256 + ch * 8); } }
; #pragma unroll
;             for (int m = 0; m < 8; ++m) { acc[m][0] = acc[m][0] * gC; acc[m][1] = acc[m][1] * gC; }
; #pragma unroll
;             for (int ks = 0; ks < 4; ++ks) {
;                 const int rho = 8 * ks + 2 * g, lo8 = (qi >> 2) * 32 + (qi & 3) * 8;
;                 bf16x8 bfr[2];
; #pragma unroll
;                 for (int nt = 0; nt < 2; ++nt) { const LAS unsigned char* p = Vt + rho * 2112 + (2 * wave + nt) * 128 + lo8; bfr[nt] = cat8(tr16(p), tr16(p + 2112)); }
; #pragma unroll
;                 for (int m = 0; m < 8; ++m) { const LAS unsigned char* p = Kt + rho * 1088 + m * 128 + lo8; const bf16x8 af = cat8(tr16(p), tr16(p + 1088));
;                     acc[m][0] = mfma16(af, bfr[0], acc[m][0]); acc[m][1] = mfma16(af, bfr[1], acc[m][1]); }
;             }
	v_mfma_f32_16x16x32_bf16 v[64:67], v[92:95], v[64:67], v[10:13]
	global_load_dwordx4 v[2:5], v[6:7], off
	s_nop 0
	global_load_dwordx4 v[6:9], v[8:9], off
	v_add_u32_e32 v10, s30, v173
	v_mad_i64_i32 v[100:101], s[50:51], v10, s33, v[42:43]
	v_mfma_f32_16x16x32_bf16 v[56:59], v[84:87], v[80:83], v[56:59]
	v_mov_b32_e32 v10, 0x4200
	v_mad_u32_u24 v10, v111, s73, v10
	v_addc_co_u32_e32 v41, vcc, 0, v41, vcc
	v_mfma_f32_16x16x32_bf16 v[60:63], v[88:91], v[80:83], v[60:63]
	v_add_u32_e32 v205, v115, v10
	v_mfma_f32_16x16x32_bf16 v[80:83], v[92:95], v[80:83], v[16:19]
	ds_read_b64_tr_b16 v[10:11], v103 offset:8704
	ds_read_b64_tr_b16 v[12:13], v103 offset:9792
	ds_read_b64_tr_b16 v[84:85], v205 offset:34816
	ds_read_b64_tr_b16 v[86:87], v205 offset:36928
	ds_read_b64_tr_b16 v[90:91], v205 offset:37056
	ds_read_b64_tr_b16 v[88:89], v205 offset:34944
	ds_read_b64_tr_b16 v[92:93], v103 offset:8832
	ds_read_b64_tr_b16 v[104:105], v103 offset:8960
	ds_read_b64_tr_b16 v[118:119], v103 offset:9088
	ds_read_b64_tr_b16 v[94:95], v103 offset:9920
	ds_read_b64_tr_b16 v[106:107], v103 offset:10048
	ds_read_b64_tr_b16 v[120:121], v103 offset:10176
	v_lshl_add_u64 v[16:17], v[100:101], 0, s[62:63]
	v_lshl_add_u64 v[16:17], v[16:17], 0, s[36:37]
	v_add_u32_e32 v18, s30, v174
	v_lshl_add_u64 v[14:15], v[16:17], 0, v[14:15]
	v_mad_i64_i32 v[18:19], s[36:37], v18, s33, v[42:43]
	v_add_co_u32_e32 v14, vcc, s49, v14
	v_lshl_add_u64 v[18:19], v[18:19], 0, s[62:63]
	s_nop 0
	v_addc_co_u32_e32 v15, vcc, 0, v15, vcc
	v_lshl_add_u64 v[18:19], v[18:19], 0, v[182:183]
	s_waitcnt lgkmcnt(8)
	v_mfma_f32_16x16x32_bf16 v[122:125], v[10:13], v[84:87], v[32:35]
	s_waitcnt lgkmcnt(6)
	v_mfma_f32_16x16x32_bf16 v[96:99], v[10:13], v[88:91], v[96:99]
	global_load_dwordx4 v[10:13], v[40:41], off
	s_nop 0
	global_load_dwordx4 v[14:17], v[14:15], off
	s_waitcnt lgkmcnt(2)
	v_mfma_f32_16x16x32_bf16 v[34:37], v[92:95], v[84:87], v[36:39]
	v_mfma_f32_16x16x32_bf16 v[38:41], v[92:95], v[88:91], v[20:23]
	s_nop 2
	v_add_co_u32_e32 v22, vcc, s40, v18
	v_add_u32_e32 v18, s30, v175
	s_nop 0
	v_addc_co_u32_e32 v23, vcc, 0, v19, vcc
	v_mad_i64_i32 v[18:19], s[36:37], v18, s33, v[42:43]
	s_waitcnt lgkmcnt(1)
	v_mfma_f32_16x16x32_bf16 v[92:95], v[104:107], v[88:91], v[24:27]
	s_nop 2
	v_lshl_add_u64 v[24:25], v[18:19], 0, s[62:63]
	ds_read_b64_tr_b16 v[18:19], v103 offset:9216
	ds_read_b64_tr_b16 v[20:21], v103 offset:10304
	v_mfma_f32_16x16x32_bf16 v[44:47], v[104:107], v[84:87], v[44:47]
	v_lshl_add_u64 v[24:25], v[24:25], 0, v[182:183]
	v_add_co_u32_e32 v24, vcc, s40, v24
	s_waitcnt lgkmcnt(2)
	v_mfma_f32_16x16x32_bf16 v[104:107], v[118:121], v[84:87], v[48:51]
	v_addc_co_u32_e32 v25, vcc, 0, v25, vcc
	v_mfma_f32_16x16x32_bf16 v[118:121], v[118:121], v[88:91], v[28:31]
	ds_read_b64_tr_b16 v[26:27], v103 offset:9344
	s_nop 1
	ds_read_b64_tr_b16 v[30:31], v103 offset:9472
	ds_read_b64_tr_b16 v[48:49], v103 offset:9600
	ds_read_b64_tr_b16 v[28:29], v103 offset:10432
	ds_read_b64_tr_b16 v[32:33], v103 offset:10560
	ds_read_b64_tr_b16 v[50:51], v103 offset:10688
	s_waitcnt lgkmcnt(6)
	v_mfma_f32_16x16x32_bf16 v[130:133], v[18:21], v[88:91], v[52:55]
	s_nop 2
	v_add_u32_e32 v52, s30, v176
	v_mad_i64_i32 v[52:53], s[36:37], v52, s33, v[42:43]
	s_waitcnt lgkmcnt(2)
	v_mfma_f32_16x16x32_bf16 v[134:137], v[26:29], v[84:87], v[72:75]
	v_lshl_add_u64 v[52:53], v[52:53], 0, s[62:63]
	v_lshl_add_u64 v[52:53], v[52:53], 0, v[182:183]
	v_mfma_f32_16x16x32_bf16 v[138:141], v[26:29], v[88:91], v[56:59]
	v_add_u32_e32 v28, s30, v177
	v_mad_i64_i32 v[28:29], s[36:37], v28, s33, v[42:43]
	v_add_co_u32_e32 v26, vcc, s40, v52
	v_lshl_add_u64 v[28:29], v[28:29], 0, s[62:63]
	s_nop 0
	v_addc_co_u32_e32 v27, vcc, 0, v53, vcc
	v_lshl_add_u64 v[28:29], v[28:29], 0, v[182:183]
	s_waitcnt lgkmcnt(1)
	v_mfma_f32_16x16x32_bf16 v[142:145], v[30:33], v[84:87], v[76:79]
	v_add_u32_e32 v58, s30, v178
	v_mfma_f32_16x16x32_bf16 v[160:163], v[30:33], v[88:91], v[60:63]
	v_add_co_u32_e32 v30, vcc, s40, v28
	s_nop 1
	v_addc_co_u32_e32 v31, vcc, 0, v29, vcc
	v_mfma_f32_16x16x32_bf16 v[126:129], v[18:21], v[84:87], v[68:71]
	global_load_dwordx4 v[18:21], v[22:23], off
	s_nop 0
	global_load_dwordx4 v[22:25], v[24:25], off
	s_nop 0
	global_load_dwordx4 v[26:29], v[26:27], off
	s_nop 0
	global_load_dwordx4 v[30:33], v[30:31], off
	s_waitcnt lgkmcnt(0)
	v_mfma_f32_16x16x32_bf16 v[164:167], v[48:51], v[84:87], v[64:67]
	v_mfma_f32_16x16x32_bf16 v[168:171], v[48:51], v[88:91], v[80:83]
	ds_read_b64_tr_b16 v[54:55], v103 offset:17408
	ds_read_b64_tr_b16 v[56:57], v103 offset:18496
	ds_read_b64_tr_b16 v[206:207], v205 offset:51712
	ds_read_b64_tr_b16 v[208:209], v205 offset:53824
	ds_read_b64_tr_b16 v[228:229], v205 offset:53952
	ds_read_b64_tr_b16 v[226:227], v205 offset:51840
	ds_read_b64_tr_b16 v[62:63], v103 offset:17536
	ds_read_b64_tr_b16 v[70:71], v103 offset:17664
	ds_read_b64_tr_b16 v[78:79], v103 offset:17792
	ds_read_b64_tr_b16 v[64:65], v103 offset:18624
	ds_read_b64_tr_b16 v[72:73], v103 offset:18752
	ds_read_b64_tr_b16 v[80:81], v103 offset:18880
	v_mad_i64_i32 v[48:49], s[36:37], v58, s33, v[42:43]
	v_lshl_add_u64 v[48:49], v[48:49], 0, s[62:63]
	v_add_u32_e32 v66, s30, v179
	v_lshl_add_u64 v[48:49], v[48:49], 0, v[182:183]
	s_waitcnt lgkmcnt(2)
; #define LAS __attribute__((address_space(3)))
; __device__ __forceinline__ unsigned pk2(float lo, float hi) { const f32x2 v = {lo, hi}; return __builtin_bit_cast(unsigned, __builtin_convertvector(v, bf16x2_t)); }
; __device__ __forceinline__ s16x4 tr16(const LAS unsigned char* p) { return __builtin_bit_cast(s16x4, __builtin_amdgcn_ds_read_tr16_b64_v4i16((LAS s16x4*)p)); }
; __device__ __forceinline__ bf16x8 cat8(s16x4 lo, s16x4 hi) { return __builtin_shufflevector(lo, hi, 0, 1, 2, 3, 4, 5, 6, 7); }
; __device__ __forceinline__ f32x4 mfma16(bf16x8 a, bf16x8 b, f32x4 c) { return __builtin_amdgcn_mfma_f32_16x16x32_bf16(a, b, c, 0, 0, 0); }
; __device__ __forceinline__ void ret_scan(const bf16* proj, bf16* ST, bf16* FS, const float* dexp, LAS unsigned char* lds, int vb, int nb, int tid_in, int wave) {
;     ...
;             for (int m = 0; m < 8; ++m) { acc[m][0] = acc[m][0] * gC; acc[m][1] = acc[m][1] * gC; }
; #pragma unroll
;             for (int ks = 0; ks < 4; ++ks) {
;                 const int rho = 8 * ks + 2 * g, lo8 = (qi >> 2) * 32 + (qi & 3) * 8;
;                 bf16x8 bfr[2];
; #pragma unroll
;                 for (int nt = 0; nt < 2; ++nt) { const LAS unsigned char* p = Vt + rho * 2112 + (2 * wave + nt) * 128 + lo8; bfr[nt] = cat8(tr16(p), tr16(p + 2112)); }
; #pragma unroll
;                 for (int m = 0; m < 8; ++m) { const LAS unsigned char* p = Kt + rho * 1088 + m * 128 + lo8; const bf16x8 af = cat8(tr16(p), tr16(p + 1088));
;                     acc[m][0] = mfma16(af, bfr[0], acc[m][0]); acc[m][1] = mfma16(af, bfr[1], acc[m][1]); }
;             }
;             dst_prev = step < 15 ? ST + ((size_t)(((base >> 7) + tgt) * 8 + h) * 2 + dir) * 65536 : FS + ((size_t)((vs - 8) * 8 + h) * 2 + dir) * 65536;
; #pragma unroll
;             for (int m = 0; m < 8; ++m)
; #pragma unroll
;                 for (int nt = 0; nt < 2; ++nt) { stq[m][nt].x = pk2(acc[m][nt].x, acc[m][nt].y); stq[m][nt].y = pk2(acc[m][nt].z, acc[m][nt].w); }
	v_mfma_f32_16x16x32_bf16 v[58:61], v[62:65], v[206:209], v[34:37]
	v_add_co_u32_e32 v48, vcc, s40, v48
	v_add_u32_e32 v90, s30, v181
	s_nop 0
	v_mad_i64_i32 v[34:35], s[36:37], v66, s33, v[42:43]
	v_lshl_add_u64 v[34:35], v[34:35], 0, s[62:63]
	v_addc_co_u32_e32 v49, vcc, 0, v49, vcc
	v_lshl_add_u64 v[34:35], v[34:35], 0, v[182:183]
	v_mfma_f32_16x16x32_bf16 v[62:65], v[62:65], v[226:229], v[38:41]
	s_nop 2
	v_add_co_u32_e32 v38, vcc, s40, v34
	s_waitcnt lgkmcnt(1)
	v_mfma_f32_16x16x32_bf16 v[66:69], v[70:73], v[206:209], v[44:47]
	v_addc_co_u32_e32 v39, vcc, 0, v35, vcc
	global_load_dwordx4 v[34:37], v[48:49], off
	s_nop 0
	global_load_dwordx4 v[38:41], v[38:39], off
	v_add_u32_e32 v44, s30, v180
	v_mad_i64_i32 v[44:45], s[36:37], v44, s33, v[42:43]
	v_lshl_add_u64 v[48:49], v[44:45], 0, s[62:63]
	ds_read_b64_tr_b16 v[44:45], v103 offset:17920
	ds_read_b64_tr_b16 v[46:47], v103 offset:19008
	v_lshl_add_u64 v[48:49], v[48:49], 0, v[182:183]
	v_mad_i64_i32 v[42:43], s[30:31], v90, s33, v[42:43]
	v_add_co_u32_e32 v48, vcc, s40, v48
	v_lshl_add_u64 v[42:43], v[42:43], 0, s[62:63]
	s_nop 0
	v_addc_co_u32_e32 v49, vcc, 0, v49, vcc
	v_lshl_add_u64 v[42:43], v[42:43], 0, v[182:183]
	s_waitcnt lgkmcnt(0)
	v_mfma_f32_16x16x32_bf16 v[82:85], v[44:47], v[206:209], v[126:129]
	s_and_b32 s30, s42, 15
	s_add_i32 s30, s56, s30
	s_lshl_b32 s30, s30, 3
	v_mfma_f32_16x16x32_bf16 v[86:89], v[44:47], v[226:229], v[130:133]
	v_add_co_u32_e32 v46, vcc, s40, v42
	v_lshl_or_b32 v182, v110, 2, s64
	s_nop 0
	v_addc_co_u32_e32 v47, vcc, 0, v43, vcc
	v_mfma_f32_16x16x32_bf16 v[50:53], v[54:57], v[206:209], v[122:125]
	s_or_b32 s30, s30, s47
	s_ashr_i32 s31, s30, 31
	s_lshl_b64 s[30:31], s[30:31], 18
	v_mfma_f32_16x16x32_bf16 v[54:57], v[54:57], v[226:229], v[96:99]
	s_add_u32 s50, s57, s30
	s_addc_u32 s51, s58, s31
	v_cvt_pk_bf16_f32 v122, v58, v59
	v_mfma_f32_16x16x32_bf16 v[70:73], v[70:73], v[226:229], v[92:95]
	v_cvt_pk_bf16_f32 v123, v60, v61
	v_cvt_pk_bf16_f32 v124, v62, v63
	v_cvt_pk_bf16_f32 v125, v64, v65
	v_mfma_f32_16x16x32_bf16 v[74:77], v[78:81], v[206:209], v[104:107]
	v_cvt_pk_bf16_f32 v126, v66, v67
	v_cvt_pk_bf16_f32 v127, v68, v69
	s_nop 1
	v_cvt_pk_bf16_f32 v128, v70, v71
	v_mfma_f32_16x16x32_bf16 v[78:81], v[78:81], v[226:229], v[118:121]
	ds_read_b64_tr_b16 v[94:95], v103 offset:18048
	ds_read_b64_tr_b16 v[104:105], v103 offset:18176
	s_nop 0
	ds_read_b64_tr_b16 v[118:119], v103 offset:18304
	ds_read_b64_tr_b16 v[96:97], v103 offset:19136
	ds_read_b64_tr_b16 v[106:107], v103 offset:19264
	ds_read_b64_tr_b16 v[120:121], v103 offset:19392
	global_load_dwordx4 v[42:45], v[48:49], off
	s_nop 0
	global_load_dwordx4 v[46:49], v[46:47], off
	v_cvt_pk_bf16_f32 v129, v72, v73
	s_waitcnt lgkmcnt(2)
	v_mfma_f32_16x16x32_bf16 v[90:93], v[94:97], v[206:209], v[134:137]
	v_cvt_pk_bf16_f32 v130, v74, v75
	v_cvt_pk_bf16_f32 v131, v76, v77
	v_cvt_pk_bf16_f32 v132, v78, v79
	v_mfma_f32_16x16x32_bf16 v[94:97], v[94:97], v[226:229], v[138:141]
	v_cvt_pk_bf16_f32 v133, v80, v81
	v_cvt_pk_bf16_f32 v134, v82, v83
	v_cvt_pk_bf16_f32 v135, v84, v85
	s_waitcnt lgkmcnt(1)
	v_mfma_f32_16x16x32_bf16 v[98:101], v[104:107], v[206:209], v[142:145]
	v_cvt_pk_bf16_f32 v136, v86, v87
	v_cvt_pk_bf16_f32 v137, v88, v89
	v_cvt_pk_bf16_f32 v138, v90, v91
	v_mfma_f32_16x16x32_bf16 v[102:105], v[104:107], v[226:229], v[160:163]
	v_cvt_pk_bf16_f32 v139, v92, v93
	v_cvt_pk_bf16_f32 v140, v94, v95
	v_cvt_pk_bf16_f32 v141, v96, v97
	s_waitcnt lgkmcnt(0)
	v_mfma_f32_16x16x32_bf16 v[106:109], v[118:121], v[206:209], v[164:167]
	v_mul_u32_u24_e32 v209, 0x440, v111
	v_lshl_or_b32 v160, v149, 8, s45
	v_or_b32_e32 v162, 0x1000, v160
	v_mul_u32_u24_e32 v165, 0x880, v110
	v_mul_u32_u24_e32 v167, 0x840, v111
	v_mfma_f32_16x16x32_bf16 v[110:113], v[118:121], v[226:229], v[168:171]
	v_cvt_pk_bf16_f32 v118, v50, v51
	v_cvt_pk_bf16_f32 v119, v52, v53
	v_cvt_pk_bf16_f32 v120, v54, v55
	v_cvt_pk_bf16_f32 v121, v56, v57
	v_cvt_pk_bf16_f32 v142, v98, v99
	v_cvt_pk_bf16_f32 v143, v100, v101
	v_cvt_pk_bf16_f32 v144, v102, v103
	v_cvt_pk_bf16_f32 v145, v104, v105
	v_cvt_pk_bf16_f32 v168, v106, v107
	v_cvt_pk_bf16_f32 v169, v108, v109
	v_cvt_pk_bf16_f32 v170, v110, v111
	v_cvt_pk_bf16_f32 v171, v112, v113
	v_ashrrev_i32_e32 v161, 31, v160
	v_ashrrev_i32_e32 v163, 31, v162
	v_lshlrev_b32_e32 v182, 1, v182
	s_lshl_b32 s62, s43, 1
	s_lshl_b32 s36, s64, 1
	v_lshlrev_b32_e32 v164, 1, v114
	v_lshlrev_b32_e32 v166, 1, v116
	v_add_u32_e32 v206, v115, v210
	v_add_u32_e32 v207, v117, v165
	v_add_u32_e32 v208, v115, v167
	v_add_u32_e32 v209, v117, v209
	s_waitcnt vmcnt(0)
	s_branch .LBB0_416

; #define LAS __attribute__((address_space(3)))
; __device__ __forceinline__ unsigned pk2(float lo, float hi) { const f32x2 v = {lo, hi}; return __builtin_bit_cast(unsigned, __builtin_convertvector(v, bf16x2_t)); }
; __device__ __forceinline__ int trw_off(int row, int c8  , int GP) { return (row >> 2) * GP + (((c8 >> 1) * 4 + (row & 3)) * 32) + (c8 & 1) * 16; }
; __device__ __forceinline__ void ret_scan(const bf16* proj, bf16* ST, bf16* FS, const float* dexp, LAS unsigned char* lds, int vb, int nb, int tid_in, int wave) {
;     ...
;             if (step < nsteps) {
;                 __syncthreads();
; #pragma unroll
;                 for (int i = 0; i < 4; ++i) { const int id = tid + 512 * i, j = id >> 4, ch = id & 15;
;                     v4u val = kr[i];
;                     const float z = __expf(lg * (float)(dir == 0 ? 127 - j : j));
;                     val.x = pk2(bflo(val.x) * z, bfhi(val.x) * z); val.y = pk2(bflo(val.y) * z, bfhi(val.y) * z); val.z = pk2(bflo(val.z) * z, bfhi(val.z) * z); val.w = pk2(bflo(val.w) * z, bfhi(val.w) * z);
;                     *(LAS v4u*)(Kt + trw_off(j, ch, 1088)) = val; }
; #pragma unroll
;                 for (int i = 0; i < 8; ++i) { const int id = tid + 512 * i, j = id >> 5, ch = id & 31; *(LAS v4u*)(Vt + trw_off(j, ch, 2112)) = vr[i]; }
;                 __syncthreads();
.LBB0_416:
	s_cmp_ge_u32 s59, s52
	s_cbranch_scc1 .LBB0_418
	s_waitcnt vmcnt(27)
	v_lshlrev_b32_e32 v114, 16, v2
	v_and_b32_e32 v115, 0xffff0000, v2
	v_lshlrev_b32_e32 v116, 16, v3
	v_and_b32_e32 v117, 0xffff0000, v3
	v_pk_mul_f32 v[114:115], v[150:151], v[114:115]
	v_pk_mul_f32 v[116:117], v[150:151], v[116:117]
	v_cvt_pk_bf16_f32 v114, v114, v115
	v_cvt_pk_bf16_f32 v115, v116, v117
	v_lshlrev_b32_e32 v116, 16, v4
	v_and_b32_e32 v117, 0xffff0000, v4
	v_lshlrev_b32_e32 v210, 16, v5
	v_and_b32_e32 v211, 0xffff0000, v5
	v_pk_mul_f32 v[116:117], v[150:151], v[116:117]
	v_pk_mul_f32 v[210:211], v[150:151], v[210:211]
	v_cvt_pk_bf16_f32 v116, v116, v117
	v_cvt_pk_bf16_f32 v117, v210, v211
	s_barrier
	ds_write_b128 v185, v[114:117]
	s_waitcnt vmcnt(26)
	v_lshlrev_b32_e32 v114, 16, v6
	v_and_b32_e32 v115, 0xffff0000, v6
	v_lshlrev_b32_e32 v116, 16, v7
	v_and_b32_e32 v117, 0xffff0000, v7
	v_pk_mul_f32 v[114:115], v[152:153], v[114:115]
	v_pk_mul_f32 v[116:117], v[152:153], v[116:117]
	v_cvt_pk_bf16_f32 v114, v114, v115
	v_cvt_pk_bf16_f32 v115, v116, v117
	v_lshlrev_b32_e32 v116, 16, v8
	v_and_b32_e32 v117, 0xffff0000, v8
	v_lshlrev_b32_e32 v210, 16, v9
	v_and_b32_e32 v211, 0xffff0000, v9
	v_pk_mul_f32 v[116:117], v[152:153], v[116:117]
	v_pk_mul_f32 v[210:211], v[152:153], v[210:211]
	v_cvt_pk_bf16_f32 v116, v116, v117
	v_cvt_pk_bf16_f32 v117, v210, v211
	ds_write_b128 v186, v[114:117]
	s_waitcnt vmcnt(25)
	v_lshlrev_b32_e32 v114, 16, v10
	v_and_b32_e32 v115, 0xffff0000, v10
	v_lshlrev_b32_e32 v116, 16, v11
	v_and_b32_e32 v117, 0xffff0000, v11
	v_pk_mul_f32 v[114:115], v[154:155], v[114:115]
	v_pk_mul_f32 v[116:117], v[154:155], v[116:117]
	v_cvt_pk_bf16_f32 v114, v114, v115
	v_cvt_pk_bf16_f32 v115, v116, v117
	v_lshlrev_b32_e32 v116, 16, v12
	v_and_b32_e32 v117, 0xffff0000, v12
	v_lshlrev_b32_e32 v210, 16, v13
	v_and_b32_e32 v211, 0xffff0000, v13
	v_pk_mul_f32 v[116:117], v[154:155], v[116:117]
	v_pk_mul_f32 v[210:211], v[154:155], v[210:211]
	v_cvt_pk_bf16_f32 v116, v116, v117
	v_cvt_pk_bf16_f32 v117, v210, v211
	ds_write_b128 v189, v[114:117]
	s_waitcnt vmcnt(24)
	v_lshlrev_b32_e32 v114, 16, v14
	v_and_b32_e32 v115, 0xffff0000, v14
	v_lshlrev_b32_e32 v116, 16, v15
	v_and_b32_e32 v117, 0xffff0000, v15
	v_pk_mul_f32 v[114:115], v[156:157], v[114:115]
	v_pk_mul_f32 v[116:117], v[156:157], v[116:117]
	v_cvt_pk_bf16_f32 v114, v114, v115
	v_cvt_pk_bf16_f32 v115, v116, v117
	v_lshlrev_b32_e32 v116, 16, v16
	v_and_b32_e32 v117, 0xffff0000, v16
	v_lshlrev_b32_e32 v210, 16, v17
	v_and_b32_e32 v211, 0xffff0000, v17
	v_pk_mul_f32 v[116:117], v[156:157], v[116:117]
	v_pk_mul_f32 v[210:211], v[156:157], v[210:211]
	v_cvt_pk_bf16_f32 v116, v116, v117
	v_cvt_pk_bf16_f32 v117, v210, v211
	ds_write_b128 v190, v[114:117]
	s_waitcnt vmcnt(23)
	ds_write_b128 v192, v[18:21] offset:34816
	s_waitcnt vmcnt(22)
	ds_write_b128 v198, v[22:25] offset:34816
	s_waitcnt vmcnt(21)
	ds_write_b128 v199, v[26:29] offset:34816
	s_waitcnt vmcnt(20)
	ds_write_b128 v200, v[30:33] offset:34816
	s_waitcnt vmcnt(19)
	ds_write_b128 v201, v[34:37] offset:34816
	s_waitcnt vmcnt(18)
	ds_write_b128 v202, v[38:41] offset:34816
	s_waitcnt vmcnt(17)
	ds_write_b128 v203, v[42:45] offset:34816
	s_waitcnt vmcnt(16)
	ds_write_b128 v204, v[46:49] offset:34816
	s_waitcnt lgkmcnt(0)
	s_barrier
; __device__ __forceinline__ void ret_scan(const bf16* proj, bf16* ST, bf16* FS, const float* dexp, LAS unsigned char* lds, int vb, int nb, int tid_in, int wave) {
;     ...
;             if (step > 0) {
; #pragma unroll
;                 for (int m = 0; m < 8; ++m)
; #pragma unroll
;                     for (int nt = 0; nt < 2; ++nt) { const int v = (2 * wave + nt) * 16 + qi, d0 = dsl * 128 + m * 16 + 4 * g; *(v2u*)(dst_prev + v * 256 + d0) = stq[m][nt]; }
;             }
;             if (step == nsteps) break;
;             if (step + 1 < nsteps) { const int n1 = dir == 0 ? step + 1 : N - 2 - step, rowb = base + n1 * 128;
; #pragma unroll
;                 for (int i = 0; i < 4; ++i) { const int id = tid + 512 * i, j = id >> 4, ch = id & 15; kr[i] = *(const v4u*)(proj + (size_t)(rowb + j) * NIN + C_RK + h * 256 + dsl * 128 + ch * 8); }
; #pragma unroll
;                 for (int i = 0; i < 8; ++i) { const int id = tid + 512 * i, j = id >> 5, ch = id & 31; vr[i] = *(const v4u*)(proj + (size_t)(rowb + j) * NIN + C_RV + h * 256 + ch * 8); } }
;     ...
;             dst_prev = step < 15 ? ST + ((size_t)(((base >> 7) + tgt) * 8 + h) * 2 + dir) * 65536 : FS + ((size_t)((vs - 8) * 8 + h) * 2 + dir) * 65536;
.LBB0_418:
	s_cmp_eq_u32 s59, s52
	v_lshl_add_u64 v[114:115], s[50:51], 0, v[182:183]
	s_cselect_b64 s[42:43], -1, 0
	v_lshl_add_u64 v[116:117], v[160:161], 1, v[114:115]
	v_lshl_add_u64 v[114:115], v[162:163], 1, v[114:115]
	s_add_i32 s64, s59, 1
	s_and_b64 vcc, exec, s[42:43]
	s_cbranch_vccnz .Lrs_last
	s_cmp_ge_u32 s64, s52
	s_cbranch_scc1 .Lrs_noload
	s_sub_i32 s37, 14, s59
	s_and_b64 s[30:31], s[4:5], exec
	s_cselect_b32 s30, s64, s37
	s_lshl_b32 s30, s30, 7
	s_add_i32 s50, s30, s53
	v_add_u32_e32 v2, s50, v1
	v_mov_b64_e32 v[42:43], s[6:7]
	v_mad_i64_i32 v[2:3], s[30:31], v2, s33, v[42:43]
	v_lshl_add_u64 v[2:3], v[2:3], 0, s[62:63]
	s_mov_b32 s37, s63
	v_add_u32_e32 v4, s50, v147
	v_lshl_add_u64 v[2:3], v[2:3], 0, s[36:37]
	v_mov_b32_e32 v165, v183
	v_mad_i64_i32 v[4:5], s[30:31], v4, s33, v[42:43]
	v_lshl_add_u64 v[2:3], v[2:3], 0, v[164:165]
	v_lshl_add_u64 v[4:5], v[4:5], 0, s[62:63]
	v_add_u32_e32 v10, s50, v172
	v_add_co_u32_e32 v2, vcc, 0x4000, v2
	v_lshl_add_u64 v[4:5], v[4:5], 0, s[36:37]
	v_mad_i64_i32 v[10:11], s[30:31], v10, s33, v[42:43]
	v_addc_co_u32_e32 v3, vcc, 0, v3, vcc
	v_lshl_add_u64 v[4:5], v[4:5], 0, v[164:165]
	v_lshl_add_u64 v[10:11], v[10:11], 0, s[62:63]
	v_add_u32_e32 v12, s50, v173
	v_add_co_u32_e32 v6, vcc, 0x4000, v4
	v_lshl_add_u64 v[10:11], v[10:11], 0, s[36:37]
	v_mad_i64_i32 v[12:13], s[30:31], v12, s33, v[42:43]
	v_addc_co_u32_e32 v7, vcc, 0, v5, vcc
	v_lshl_add_u64 v[10:11], v[10:11], 0, v[164:165]
	v_lshl_add_u64 v[12:13], v[12:13], 0, s[62:63]
	v_add_co_u32_e32 v10, vcc, 0x4000, v10
	v_lshl_add_u64 v[12:13], v[12:13], 0, s[36:37]
	v_add_u32_e32 v18, s50, v174
	v_addc_co_u32_e32 v11, vcc, 0, v11, vcc
	v_lshl_add_u64 v[12:13], v[12:13], 0, v[164:165]
	v_mad_i64_i32 v[18:19], s[30:31], v18, s33, v[42:43]
	v_add_co_u32_e32 v14, vcc, 0x4000, v12
	v_lshl_add_u64 v[18:19], v[18:19], 0, s[62:63]
	v_mov_b32_e32 v167, v183
	v_add_u32_e32 v20, s50, v175
	v_addc_co_u32_e32 v15, vcc, 0, v13, vcc
	v_lshl_add_u64 v[18:19], v[18:19], 0, v[166:167]
	v_mad_i64_i32 v[20:21], s[30:31], v20, s33, v[42:43]
	v_add_co_u32_e32 v18, vcc, 0x5000, v18
	v_lshl_add_u64 v[20:21], v[20:21], 0, s[62:63]
	v_add_u32_e32 v26, s50, v176
	v_addc_co_u32_e32 v19, vcc, 0, v19, vcc
	v_lshl_add_u64 v[20:21], v[20:21], 0, v[166:167]
	v_mad_i64_i32 v[26:27], s[30:31], v26, s33, v[42:43]
	v_add_co_u32_e32 v22, vcc, 0x5000, v20
	v_lshl_add_u64 v[26:27], v[26:27], 0, s[62:63]
	v_add_u32_e32 v28, s50, v177
	v_addc_co_u32_e32 v23, vcc, 0, v21, vcc
	v_lshl_add_u64 v[26:27], v[26:27], 0, v[166:167]
	v_mad_i64_i32 v[28:29], s[30:31], v28, s33, v[42:43]
	v_add_co_u32_e32 v26, vcc, 0x5000, v26
	v_lshl_add_u64 v[28:29], v[28:29], 0, s[62:63]
	v_add_u32_e32 v34, s50, v178
	v_addc_co_u32_e32 v27, vcc, 0, v27, vcc
	v_lshl_add_u64 v[28:29], v[28:29], 0, v[166:167]
	v_mad_i64_i32 v[34:35], s[30:31], v34, s33, v[42:43]
	v_add_co_u32_e32 v30, vcc, 0x5000, v28
	v_lshl_add_u64 v[34:35], v[34:35], 0, s[62:63]
	v_add_u32_e32 v36, s50, v179
	v_addc_co_u32_e32 v31, vcc, 0, v29, vcc
	v_lshl_add_u64 v[34:35], v[34:35], 0, v[166:167]
	v_mad_i64_i32 v[36:37], s[30:31], v36, s33, v[42:43]
	v_add_co_u32_e32 v34, vcc, 0x5000, v34
	v_lshl_add_u64 v[36:37], v[36:37], 0, s[62:63]
	v_add_u32_e32 v44, s50, v180
	v_addc_co_u32_e32 v35, vcc, 0, v35, vcc
	v_lshl_add_u64 v[36:37], v[36:37], 0, v[166:167]
	v_mad_i64_i32 v[44:45], s[30:31], v44, s33, v[42:43]
	v_add_co_u32_e32 v38, vcc, 0x5000, v36
	v_lshl_add_u64 v[44:45], v[44:45], 0, s[62:63]
	v_add_u32_e32 v46, s50, v181
	v_addc_co_u32_e32 v39, vcc, 0, v37, vcc
	v_lshl_add_u64 v[44:45], v[44:45], 0, v[166:167]
	v_mad_i64_i32 v[42:43], s[30:31], v46, s33, v[42:43]
	v_add_co_u32_e32 v44, vcc, 0x5000, v44
	v_lshl_add_u64 v[42:43], v[42:43], 0, s[62:63]
	s_nop 0
	v_addc_co_u32_e32 v45, vcc, 0, v45, vcc
	v_lshl_add_u64 v[42:43], v[42:43], 0, v[166:167]
	v_add_co_u32_e32 v46, vcc, 0x5000, v42
	global_load_dwordx4 v[2:5], v[2:3], off
	s_nop 0
	global_load_dwordx4 v[6:9], v[6:7], off
	v_addc_co_u32_e32 v47, vcc, 0, v43, vcc
	global_load_dwordx4 v[10:13], v[10:11], off
	s_nop 0
	global_load_dwordx4 v[14:17], v[14:15], off
	s_nop 0
	global_load_dwordx4 v[18:21], v[18:19], off
	s_nop 0
	global_load_dwordx4 v[22:25], v[22:23], off
	s_nop 0
	global_load_dwordx4 v[26:29], v[26:27], off
	s_nop 0
	global_load_dwordx4 v[30:33], v[30:31], off
	s_nop 0
	global_load_dwordx4 v[34:37], v[34:35], off
	s_nop 0
	global_load_dwordx4 v[38:41], v[38:39], off
	s_nop 0
	global_load_dwordx4 v[42:45], v[44:45], off
	s_nop 0
	global_load_dwordx4 v[46:49], v[46:47], off
	global_store_dwordx2 v[116:117], v[118:119], off
	global_store_dwordx2 v[114:115], v[120:121], off
	global_store_dwordx2 v[116:117], v[122:123], off offset:32
	global_store_dwordx2 v[114:115], v[124:125], off offset:32
	global_store_dwordx2 v[116:117], v[126:127], off offset:64
	global_store_dwordx2 v[114:115], v[128:129], off offset:64
	global_store_dwordx2 v[116:117], v[130:131], off offset:96
	global_store_dwordx2 v[114:115], v[132:133], off offset:96
	global_store_dwordx2 v[116:117], v[134:135], off offset:128
	global_store_dwordx2 v[114:115], v[136:137], off offset:128
	global_store_dwordx2 v[116:117], v[138:139], off offset:160
	global_store_dwordx2 v[114:115], v[140:141], off offset:160
	global_store_dwordx2 v[116:117], v[142:143], off offset:192
	global_store_dwordx2 v[114:115], v[144:145], off offset:192
	global_store_dwordx2 v[116:117], v[168:169], off offset:224
	global_store_dwordx2 v[114:115], v[170:171], off offset:224
	s_branch .LBB0_414
.Lrs_last:
	global_store_dwordx2 v[116:117], v[118:119], off
	global_store_dwordx2 v[114:115], v[120:121], off
	global_store_dwordx2 v[116:117], v[122:123], off offset:32
	global_store_dwordx2 v[114:115], v[124:125], off offset:32
	global_store_dwordx2 v[116:117], v[126:127], off offset:64
	global_store_dwordx2 v[114:115], v[128:129], off offset:64
	global_store_dwordx2 v[116:117], v[130:131], off offset:96
	global_store_dwordx2 v[114:115], v[132:133], off offset:96
	global_store_dwordx2 v[116:117], v[134:135], off offset:128
	global_store_dwordx2 v[114:115], v[136:137], off offset:128
	global_store_dwordx2 v[116:117], v[138:139], off offset:160
	global_store_dwordx2 v[114:115], v[140:141], off offset:160
	global_store_dwordx2 v[116:117], v[142:143], off offset:192
	global_store_dwordx2 v[114:115], v[144:145], off offset:192
	global_store_dwordx2 v[116:117], v[168:169], off offset:224
	global_store_dwordx2 v[114:115], v[170:171], off offset:224
	s_branch .LBB0_415

; __device__ __forceinline__ unsigned pk2(float lo, float hi) { const f32x2 v = {lo, hi}; return __builtin_bit_cast(unsigned, __builtin_convertvector(v, bf16x2_t)); }
; __device__ __forceinline__ void ret_out(const bf16* proj, const bf16* ST, bf16* mixed, const float* dexp, LAS unsigned char* lds, int vb, int nb, int tid_in0, int wave) {
;     ...
;             if (dir == 0) { if (have_b) { const bf16* src = ST + ((size_t)(gc * 8 + h) * 2 + 1) * 65536;
; #pragma unroll
;                     for (int i = 0; i < 16; ++i) { const int id = tid + 512 * i; pf[i] = *(const v4u*)(src + (id >> 5) * 256 + (id & 31) * 8); } } }
;             else { const int un = unit + nb;
;                 if (un < 1536) { const int gc2 = un >> 3, h2 = un & 7, rowb2 = gc2 * 128;
; #pragma unroll
;                     for (int i = 0; i < 8; ++i) { const int id = tid + 512 * i, j = id >> 5, ch = id & 31;
;                         pf[i] = *(const v4u*)(proj + (size_t)(rowb2 + j) * NIN + C_RK + h2 * 256 + ch * 8); pf[8 + i] = *(const v4u*)(proj + (size_t)(rowb2 + j) * NIN + C_RV + h2 * 256 + ch * 8); } } }
;             if (have) {
;                 const float xi = dir == 0 ? __expf(lgf * (float)(iq + 1)) : __expf(lgb * (float)(128 - iq));
; #pragma unroll
;                 for (int kh = 0; kh < 2; ++kh) {
;                     bf16x8 qs[4];
; #pragma unroll
;                     for (int k4 = 0; k4 < 4; ++k4) { const int ks = 4 * kh + k4; const v4u q = *(const v4u*)(proj + (size_t)qrow * NIN + C_RQ + h * 256 + ks * 32 + g * 8); v4u r;
;                         r.x = pk2(bflo(q.x) * xi, bfhi(q.x) * xi); r.y = pk2(bflo(q.y) * xi, bfhi(q.y) * xi); r.z = pk2(bflo(q.z) * xi, bfhi(q.z) * xi); r.w = pk2(bflo(q.w) * xi, bfhi(q.w) * xi);
;                         qs[k4] = __builtin_bit_cast(bf16x8, r); }
.LBB0_842:
	v_mul_u32_u24_e32 v130, 0x210, v231
	v_add_u32_e32 v155, 0x10800, v130
	v_add_u32_e32 v154, 0x12900, v130
	v_add_u32_e32 v153, 0x14a00, v130
	v_add_u32_e32 v152, 0x16b00, v130
	v_add_u32_e32 v151, 0x18c00, v130
	v_add_u32_e32 v150, 0x1ad00, v130
	v_add_u32_e32 v149, 0x1ce00, v130
	v_add_u32_e32 v147, 0x1ef00, v130
	s_and_b64 vcc, exec, s[4:5]
	v_add_u32_e32 v156, v234, v130
	v_add_u32_e32 v164, v234, v155
	v_add_u32_e32 v163, v234, v154
	v_add_u32_e32 v162, v234, v153
	v_add_u32_e32 v161, v234, v152
	v_add_u32_e32 v160, v234, v151
	v_add_u32_e32 v159, v234, v150
	v_add_u32_e32 v158, v234, v149
	v_add_u32_e32 v157, v234, v147
	v_add_u32_e32 v148, 0x100, v234
	s_cbranch_vccnz .LBB0_844
	v_add_u32_e32 v130, 1, v189
	v_cvt_f32_i32_e32 v130, v130
	v_mul_f32_e32 v130, v235, v130
	v_mul_f32_e32 v130, 0x3fb8aa3b, v130
	v_exp_f32_e32 v146, v130
	global_load_dwordx4 v[130:133], v[202:203], off
	global_load_dwordx4 v[134:137], v[202:203], off offset:64
	global_load_dwordx4 v[138:141], v[202:203], off offset:128
	global_load_dwordx4 v[142:145], v[202:203], off offset:192
	s_waitcnt vmcnt(3)
	v_lshlrev_b32_e32 v174, 16, v130
	v_and_b32_e32 v175, 0xffff0000, v130
	v_pk_mul_f32 v[174:175], v[146:147], v[174:175] op_sel_hi:[0,1]
	v_cvt_pk_bf16_f32 v130, v174, v175
	v_lshlrev_b32_e32 v174, 16, v131
	v_and_b32_e32 v175, 0xffff0000, v131
	v_pk_mul_f32 v[174:175], v[146:147], v[174:175] op_sel_hi:[0,1]
	v_cvt_pk_bf16_f32 v131, v174, v175
	v_lshlrev_b32_e32 v174, 16, v132
	v_and_b32_e32 v175, 0xffff0000, v132
	v_pk_mul_f32 v[174:175], v[146:147], v[174:175] op_sel_hi:[0,1]
	v_cvt_pk_bf16_f32 v132, v174, v175
	v_lshlrev_b32_e32 v174, 16, v133
	v_and_b32_e32 v175, 0xffff0000, v133
	v_pk_mul_f32 v[174:175], v[146:147], v[174:175] op_sel_hi:[0,1]
	v_cvt_pk_bf16_f32 v133, v174, v175
	s_waitcnt vmcnt(2)
	v_lshlrev_b32_e32 v174, 16, v134
	v_and_b32_e32 v175, 0xffff0000, v134
	v_pk_mul_f32 v[174:175], v[146:147], v[174:175] op_sel_hi:[0,1]
	v_cvt_pk_bf16_f32 v134, v174, v175
	v_lshlrev_b32_e32 v174, 16, v135
	v_and_b32_e32 v175, 0xffff0000, v135
	v_pk_mul_f32 v[174:175], v[146:147], v[174:175] op_sel_hi:[0,1]
	v_cvt_pk_bf16_f32 v135, v174, v175
	v_lshlrev_b32_e32 v174, 16, v136
	v_and_b32_e32 v175, 0xffff0000, v136
	v_pk_mul_f32 v[174:175], v[146:147], v[174:175] op_sel_hi:[0,1]
	v_cvt_pk_bf16_f32 v136, v174, v175
	v_lshlrev_b32_e32 v174, 16, v137
	v_and_b32_e32 v175, 0xffff0000, v137
	v_pk_mul_f32 v[174:175], v[146:147], v[174:175] op_sel_hi:[0,1]
	v_cvt_pk_bf16_f32 v137, v174, v175
	s_waitcnt vmcnt(1)
	v_lshlrev_b32_e32 v174, 16, v138
	v_and_b32_e32 v175, 0xffff0000, v138
	v_pk_mul_f32 v[174:175], v[146:147], v[174:175] op_sel_hi:[0,1]
	v_cvt_pk_bf16_f32 v138, v174, v175
	v_lshlrev_b32_e32 v174, 16, v139
	v_and_b32_e32 v175, 0xffff0000, v139
	v_pk_mul_f32 v[174:175], v[146:147], v[174:175] op_sel_hi:[0,1]
	v_cvt_pk_bf16_f32 v139, v174, v175
	v_lshlrev_b32_e32 v174, 16, v140
	v_and_b32_e32 v175, 0xffff0000, v140
	v_pk_mul_f32 v[174:175], v[146:147], v[174:175] op_sel_hi:[0,1]
	v_cvt_pk_bf16_f32 v140, v174, v175
	v_lshlrev_b32_e32 v174, 16, v141
	v_and_b32_e32 v175, 0xffff0000, v141
	v_pk_mul_f32 v[174:175], v[146:147], v[174:175] op_sel_hi:[0,1]
	v_cvt_pk_bf16_f32 v141, v174, v175
	s_waitcnt vmcnt(0)
	v_lshlrev_b32_e32 v174, 16, v142
	v_and_b32_e32 v175, 0xffff0000, v142
	v_pk_mul_f32 v[174:175], v[146:147], v[174:175] op_sel_hi:[0,1]
	v_cvt_pk_bf16_f32 v142, v174, v175
	v_lshlrev_b32_e32 v174, 16, v143
	v_and_b32_e32 v175, 0xffff0000, v143
	v_pk_mul_f32 v[174:175], v[146:147], v[174:175] op_sel_hi:[0,1]
	v_cvt_pk_bf16_f32 v143, v174, v175
	v_lshlrev_b32_e32 v174, 16, v144
	v_and_b32_e32 v175, 0xffff0000, v144
	v_pk_mul_f32 v[174:175], v[146:147], v[174:175] op_sel_hi:[0,1]
	v_cvt_pk_bf16_f32 v144, v174, v175
	v_lshlrev_b32_e32 v174, 16, v145
	v_and_b32_e32 v175, 0xffff0000, v145
	v_pk_mul_f32 v[174:175], v[146:147], v[174:175] op_sel_hi:[0,1]
	v_cvt_pk_bf16_f32 v145, v174, v175
	s_cmp_ge_i32 s26, s15
	s_cbranch_scc1 .Lro_nopf_d0
	s_add_u32 s6, s56, s6
	s_addc_u32 s7, s57, s7
	v_and_b32_e32 v60, 0xffffff00, v233
	v_lshl_add_u64 v[2:3], v[182:183], 1, s[6:7]
	s_mov_b64 s[6:7], 0x20000
	v_add_u32_e32 v4, 0x1000, v60
	v_add_u32_e32 v10, 0x2000, v60
	v_add_u32_e32 v12, 0x3000, v60
	v_add_u32_e32 v18, 0x4000, v60
	v_add_u32_e32 v20, 0x5000, v60
	v_lshl_add_u64 v[58:59], v[2:3], 0, s[6:7]
	v_ashrrev_i32_e32 v61, 31, v60
	v_ashrrev_i32_e32 v5, 31, v4
	v_ashrrev_i32_e32 v11, 31, v10
	v_ashrrev_i32_e32 v13, 31, v12
	v_ashrrev_i32_e32 v19, 31, v18
	v_ashrrev_i32_e32 v21, 31, v20
	v_lshl_add_u64 v[2:3], v[60:61], 1, v[58:59]
	v_lshl_add_u64 v[6:7], v[4:5], 1, v[58:59]
	v_lshl_add_u64 v[10:11], v[10:11], 1, v[58:59]
	v_lshl_add_u64 v[14:15], v[12:13], 1, v[58:59]
	v_lshl_add_u64 v[18:19], v[18:19], 1, v[58:59]
	v_lshl_add_u64 v[20:21], v[20:21], 1, v[58:59]
	global_load_dwordx4 v[2:5], v[2:3], off
	s_nop 0
	global_load_dwordx4 v[6:9], v[6:7], off
	s_nop 0
	global_load_dwordx4 v[10:13], v[10:11], off
	s_nop 0
	global_load_dwordx4 v[14:17], v[14:15], off
	s_nop 0
	global_load_dwordx4 v[26:29], v[18:19], off
	global_load_dwordx4 v[30:33], v[20:21], off
	v_add_u32_e32 v18, 0x6000, v60
	v_add_u32_e32 v20, 0x7000, v60
	v_ashrrev_i32_e32 v19, 31, v18
	v_ashrrev_i32_e32 v21, 31, v20
	v_lshl_add_u64 v[18:19], v[18:19], 1, v[58:59]
	v_lshl_add_u64 v[20:21], v[20:21], 1, v[58:59]
	global_load_dwordx4 v[42:45], v[18:19], off
	global_load_dwordx4 v[46:49], v[20:21], off
	v_add_u32_e32 v18, 0x8000, v60
	v_add_u32_e32 v20, 0x9000, v60
	v_add_u32_e32 v34, 0xa000, v60
	v_add_u32_e32 v36, 0xb000, v60
	v_add_u32_e32 v50, 0xc000, v60
	v_add_u32_e32 v52, 0xd000, v60
	v_add_u32_e32 v62, 0xe000, v60
	v_add_u32_e32 v60, 0xf000, v60
	v_ashrrev_i32_e32 v19, 31, v18
	v_ashrrev_i32_e32 v21, 31, v20
	v_ashrrev_i32_e32 v35, 31, v34
	v_ashrrev_i32_e32 v37, 31, v36
	v_ashrrev_i32_e32 v51, 31, v50
	v_ashrrev_i32_e32 v53, 31, v52
	v_ashrrev_i32_e32 v63, 31, v62
	v_ashrrev_i32_e32 v61, 31, v60
	v_lshl_add_u64 v[18:19], v[18:19], 1, v[58:59]
	v_lshl_add_u64 v[22:23], v[20:21], 1, v[58:59]
	v_lshl_add_u64 v[34:35], v[34:35], 1, v[58:59]
	v_lshl_add_u64 v[38:39], v[36:37], 1, v[58:59]
	v_lshl_add_u64 v[50:51], v[50:51], 1, v[58:59]
	v_lshl_add_u64 v[54:55], v[52:53], 1, v[58:59]
	v_lshl_add_u64 v[62:63], v[62:63], 1, v[58:59]
	v_lshl_add_u64 v[64:65], v[60:61], 1, v[58:59]
	global_load_dwordx4 v[18:21], v[18:19], off
	s_nop 0
	global_load_dwordx4 v[22:25], v[22:23], off
	s_nop 0
	global_load_dwordx4 v[34:37], v[34:35], off
	s_nop 0
	global_load_dwordx4 v[38:41], v[38:39], off
	s_nop 0
	global_load_dwordx4 v[50:53], v[50:51], off
	s_nop 0
	global_load_dwordx4 v[54:57], v[54:55], off
	s_nop 0
	global_load_dwordx4 v[58:61], v[62:63], off
	s_nop 0
	global_load_dwordx4 v[62:65], v[64:65], off
; #define LAS __attribute__((address_space(3)))
; __device__ __forceinline__ f32x4 mfma16(bf16x8 a, bf16x8 b, f32x4 c) { return __builtin_amdgcn_mfma_f32_16x16x32_bf16(a, b, c, 0, 0, 0); }
; __device__ __forceinline__ void ret_out(const bf16* proj, const bf16* ST, bf16* mixed, const float* dexp, LAS unsigned char* lds, int vb, int nb, int tid_in0, int wave) {
;     ...
; #pragma unroll
;                     for (int v = 0; v < 16; ++v) {
;                         const LAS unsigned char* sp = Sx + (v * 16 + qi) * 528 + g * 16 + kh * 256;
; #pragma unroll
;                         for (int k4 = 0; k4 < 4; ++k4) o[v] = mfma16(*(const LAS bf16x8*)(sp + k4 * 64), qs[k4], o[v]);
;                         if ((v & 1) == 1) asm volatile("" ::: "memory");
;                     }
.Lro_nopf_d0:
	ds_read_b128 v[174:177], v156
	s_waitcnt lgkmcnt(0)
	v_mfma_f32_16x16x32_bf16 v[122:125], v[174:177], v[130:133], v[122:125]
	ds_read_b128 v[174:177], v156 offset:64
	s_waitcnt lgkmcnt(0)
	v_mfma_f32_16x16x32_bf16 v[122:125], v[174:177], v[134:137], v[122:125]
	ds_read_b128 v[174:177], v156 offset:128
	s_waitcnt lgkmcnt(0)
	v_mfma_f32_16x16x32_bf16 v[122:125], v[174:177], v[138:141], v[122:125]
	ds_read_b128 v[174:177], v156 offset:192
	s_waitcnt lgkmcnt(0)
	v_mfma_f32_16x16x32_bf16 v[122:125], v[174:177], v[142:145], v[122:125]
	ds_read_b128 v[174:177], v156 offset:8640
	ds_read_b128 v[178:181], v156 offset:8576
	ds_read_b128 v[232:235], v156 offset:8512
	ds_read_b128 v[236:239], v156 offset:8448
	s_waitcnt lgkmcnt(0)
	v_mfma_f32_16x16x32_bf16 v[126:129], v[236:239], v[130:133], v[126:129]
	v_mfma_f32_16x16x32_bf16 v[126:129], v[232:235], v[134:137], v[126:129]
	v_mfma_f32_16x16x32_bf16 v[126:129], v[178:181], v[138:141], v[126:129]
	v_mfma_f32_16x16x32_bf16 v[126:129], v[174:177], v[142:145], v[126:129]
	ds_read_b128 v[174:177], v156 offset:16896
	s_waitcnt lgkmcnt(0)
	v_mfma_f32_16x16x32_bf16 v[118:121], v[174:177], v[130:133], v[118:121]
	ds_read_b128 v[174:177], v156 offset:16960
	s_waitcnt lgkmcnt(0)
	v_mfma_f32_16x16x32_bf16 v[118:121], v[174:177], v[134:137], v[118:121]
	ds_read_b128 v[174:177], v156 offset:17024
	s_waitcnt lgkmcnt(0)
	v_mfma_f32_16x16x32_bf16 v[118:121], v[174:177], v[138:141], v[118:121]
	ds_read_b128 v[174:177], v156 offset:17088
	s_waitcnt lgkmcnt(0)
	v_mfma_f32_16x16x32_bf16 v[118:121], v[174:177], v[142:145], v[118:121]
	ds_read_b128 v[174:177], v156 offset:25536
	ds_read_b128 v[178:181], v156 offset:25472
	ds_read_b128 v[232:235], v156 offset:25408
	ds_read_b128 v[236:239], v156 offset:25344
	s_waitcnt lgkmcnt(0)
	v_mfma_f32_16x16x32_bf16 v[114:117], v[236:239], v[130:133], v[114:117]
	v_mfma_f32_16x16x32_bf16 v[114:117], v[232:235], v[134:137], v[114:117]
	v_mfma_f32_16x16x32_bf16 v[114:117], v[178:181], v[138:141], v[114:117]
	v_mfma_f32_16x16x32_bf16 v[114:117], v[174:177], v[142:145], v[114:117]
	ds_read_b128 v[174:177], v156 offset:33792
	s_waitcnt lgkmcnt(0)
	v_mfma_f32_16x16x32_bf16 v[110:113], v[174:177], v[130:133], v[110:113]
	ds_read_b128 v[174:177], v156 offset:33856
	s_waitcnt lgkmcnt(0)
	v_mfma_f32_16x16x32_bf16 v[110:113], v[174:177], v[134:137], v[110:113]
	ds_read_b128 v[174:177], v156 offset:33920
	s_waitcnt lgkmcnt(0)
	v_mfma_f32_16x16x32_bf16 v[110:113], v[174:177], v[138:141], v[110:113]
	ds_read_b128 v[174:177], v156 offset:33984
	s_waitcnt lgkmcnt(0)
	v_mfma_f32_16x16x32_bf16 v[110:113], v[174:177], v[142:145], v[110:113]
	ds_read_b128 v[174:177], v156 offset:42432
	ds_read_b128 v[178:181], v156 offset:42368
	ds_read_b128 v[232:235], v156 offset:42304
	ds_read_b128 v[236:239], v156 offset:42240
	s_waitcnt lgkmcnt(0)
	v_mfma_f32_16x16x32_bf16 v[106:109], v[236:239], v[130:133], v[106:109]
	v_mfma_f32_16x16x32_bf16 v[106:109], v[232:235], v[134:137], v[106:109]
	v_mfma_f32_16x16x32_bf16 v[106:109], v[178:181], v[138:141], v[106:109]
	v_mfma_f32_16x16x32_bf16 v[106:109], v[174:177], v[142:145], v[106:109]
	ds_read_b128 v[174:177], v156 offset:50688
	s_waitcnt lgkmcnt(0)
	v_mfma_f32_16x16x32_bf16 v[102:105], v[174:177], v[130:133], v[102:105]
	ds_read_b128 v[174:177], v156 offset:50752
	s_waitcnt lgkmcnt(0)
	v_mfma_f32_16x16x32_bf16 v[102:105], v[174:177], v[134:137], v[102:105]
	ds_read_b128 v[174:177], v156 offset:50816
	s_waitcnt lgkmcnt(0)
	v_mfma_f32_16x16x32_bf16 v[102:105], v[174:177], v[138:141], v[102:105]
	ds_read_b128 v[174:177], v156 offset:50880
	s_waitcnt lgkmcnt(0)
	v_mfma_f32_16x16x32_bf16 v[102:105], v[174:177], v[142:145], v[102:105]
	ds_read_b128 v[174:177], v156 offset:59328
	ds_read_b128 v[178:181], v156 offset:59264
	ds_read_b128 v[232:235], v156 offset:59200
	ds_read_b128 v[236:239], v156 offset:59136
	s_waitcnt lgkmcnt(0)
	v_mfma_f32_16x16x32_bf16 v[98:101], v[236:239], v[130:133], v[98:101]
	v_mfma_f32_16x16x32_bf16 v[98:101], v[232:235], v[134:137], v[98:101]
	v_mfma_f32_16x16x32_bf16 v[98:101], v[178:181], v[138:141], v[98:101]
	v_mfma_f32_16x16x32_bf16 v[98:101], v[174:177], v[142:145], v[98:101]
	ds_read_b128 v[174:177], v164
	s_waitcnt lgkmcnt(0)
	v_mfma_f32_16x16x32_bf16 v[94:97], v[174:177], v[130:133], v[94:97]
	ds_read_b128 v[174:177], v164 offset:64
	s_waitcnt lgkmcnt(0)
	v_mfma_f32_16x16x32_bf16 v[94:97], v[174:177], v[134:137], v[94:97]
	ds_read_b128 v[174:177], v164 offset:128
	s_waitcnt lgkmcnt(0)
	v_mfma_f32_16x16x32_bf16 v[94:97], v[174:177], v[138:141], v[94:97]
	ds_read_b128 v[174:177], v164 offset:192
	s_waitcnt lgkmcnt(0)
	v_mfma_f32_16x16x32_bf16 v[94:97], v[174:177], v[142:145], v[94:97]
	ds_read_b128 v[174:177], v163
	s_waitcnt lgkmcnt(0)
	v_mfma_f32_16x16x32_bf16 v[90:93], v[174:177], v[130:133], v[90:93]
	ds_read_b128 v[174:177], v163 offset:64
	s_waitcnt lgkmcnt(0)
	v_mfma_f32_16x16x32_bf16 v[90:93], v[174:177], v[134:137], v[90:93]
	ds_read_b128 v[174:177], v163 offset:128
	s_waitcnt lgkmcnt(0)
	v_mfma_f32_16x16x32_bf16 v[90:93], v[174:177], v[138:141], v[90:93]
	ds_read_b128 v[174:177], v163 offset:192
	s_waitcnt lgkmcnt(0)
	v_mfma_f32_16x16x32_bf16 v[90:93], v[174:177], v[142:145], v[90:93]
	ds_read_b128 v[174:177], v162
	s_waitcnt lgkmcnt(0)
	v_mfma_f32_16x16x32_bf16 v[86:89], v[174:177], v[130:133], v[86:89]
	ds_read_b128 v[174:177], v162 offset:64
	s_waitcnt lgkmcnt(0)
	v_mfma_f32_16x16x32_bf16 v[86:89], v[174:177], v[134:137], v[86:89]
	ds_read_b128 v[174:177], v162 offset:128
	s_waitcnt lgkmcnt(0)
	v_mfma_f32_16x16x32_bf16 v[86:89], v[174:177], v[138:141], v[86:89]
	ds_read_b128 v[174:177], v162 offset:192
	s_waitcnt lgkmcnt(0)
; #define LAS __attribute__((address_space(3)))
; __device__ __forceinline__ unsigned pk2(float lo, float hi) { const f32x2 v = {lo, hi}; return __builtin_bit_cast(unsigned, __builtin_convertvector(v, bf16x2_t)); }
; __device__ __forceinline__ f32x4 mfma16(bf16x8 a, bf16x8 b, f32x4 c) { return __builtin_amdgcn_mfma_f32_16x16x32_bf16(a, b, c, 0, 0, 0); }
; __device__ __forceinline__ void ret_out(const bf16* proj, const bf16* ST, bf16* mixed, const float* dexp, LAS unsigned char* lds, int vb, int nb, int tid_in0, int wave) {
;     ...
;                 for (int kh = 0; kh < 2; ++kh) {
;                     bf16x8 qs[4];
; #pragma unroll
;                     for (int k4 = 0; k4 < 4; ++k4) { const int ks = 4 * kh + k4; const v4u q = *(const v4u*)(proj + (size_t)qrow * NIN + C_RQ + h * 256 + ks * 32 + g * 8); v4u r;
;                         r.x = pk2(bflo(q.x) * xi, bfhi(q.x) * xi); r.y = pk2(bflo(q.y) * xi, bfhi(q.y) * xi); r.z = pk2(bflo(q.z) * xi, bfhi(q.z) * xi); r.w = pk2(bflo(q.w) * xi, bfhi(q.w) * xi);
;                         qs[k4] = __builtin_bit_cast(bf16x8, r); }
; #pragma unroll
;                     for (int v = 0; v < 16; ++v) {
;                         const LAS unsigned char* sp = Sx + (v * 16 + qi) * 528 + g * 16 + kh * 256;
; #pragma unroll
;                         for (int k4 = 0; k4 < 4; ++k4) o[v] = mfma16(*(const LAS bf16x8*)(sp + k4 * 64), qs[k4], o[v]);
;                         if ((v & 1) == 1) asm volatile("" ::: "memory");
;                     }
	v_mfma_f32_16x16x32_bf16 v[86:89], v[174:177], v[142:145], v[86:89]
	ds_read_b128 v[174:177], v161
	s_waitcnt lgkmcnt(0)
	v_mfma_f32_16x16x32_bf16 v[82:85], v[174:177], v[130:133], v[82:85]
	ds_read_b128 v[174:177], v161 offset:64
	s_waitcnt lgkmcnt(0)
	v_mfma_f32_16x16x32_bf16 v[82:85], v[174:177], v[134:137], v[82:85]
	ds_read_b128 v[174:177], v161 offset:128
	s_waitcnt lgkmcnt(0)
	v_mfma_f32_16x16x32_bf16 v[82:85], v[174:177], v[138:141], v[82:85]
	ds_read_b128 v[174:177], v161 offset:192
	s_waitcnt lgkmcnt(0)
	v_mfma_f32_16x16x32_bf16 v[82:85], v[174:177], v[142:145], v[82:85]
	ds_read_b128 v[174:177], v160
	s_waitcnt lgkmcnt(0)
	v_mfma_f32_16x16x32_bf16 v[78:81], v[174:177], v[130:133], v[78:81]
	ds_read_b128 v[174:177], v160 offset:64
	s_waitcnt lgkmcnt(0)
	v_mfma_f32_16x16x32_bf16 v[78:81], v[174:177], v[134:137], v[78:81]
	ds_read_b128 v[174:177], v160 offset:128
	s_waitcnt lgkmcnt(0)
	v_mfma_f32_16x16x32_bf16 v[78:81], v[174:177], v[138:141], v[78:81]
	ds_read_b128 v[174:177], v160 offset:192
	s_waitcnt lgkmcnt(0)
	v_mfma_f32_16x16x32_bf16 v[78:81], v[174:177], v[142:145], v[78:81]
	ds_read_b128 v[174:177], v159
	s_waitcnt lgkmcnt(0)
	v_mfma_f32_16x16x32_bf16 v[74:77], v[174:177], v[130:133], v[74:77]
	ds_read_b128 v[174:177], v159 offset:64
	s_waitcnt lgkmcnt(0)
	v_mfma_f32_16x16x32_bf16 v[74:77], v[174:177], v[134:137], v[74:77]
	ds_read_b128 v[174:177], v159 offset:128
	s_waitcnt lgkmcnt(0)
	v_mfma_f32_16x16x32_bf16 v[74:77], v[174:177], v[138:141], v[74:77]
	ds_read_b128 v[174:177], v159 offset:192
	s_waitcnt lgkmcnt(0)
	v_mfma_f32_16x16x32_bf16 v[74:77], v[174:177], v[142:145], v[74:77]
	ds_read_b128 v[174:177], v158
	s_waitcnt lgkmcnt(0)
	v_mfma_f32_16x16x32_bf16 v[70:73], v[174:177], v[130:133], v[70:73]
	ds_read_b128 v[174:177], v158 offset:64
	s_waitcnt lgkmcnt(0)
	v_mfma_f32_16x16x32_bf16 v[70:73], v[174:177], v[134:137], v[70:73]
	ds_read_b128 v[174:177], v158 offset:128
	s_waitcnt lgkmcnt(0)
	v_mfma_f32_16x16x32_bf16 v[70:73], v[174:177], v[138:141], v[70:73]
	ds_read_b128 v[174:177], v158 offset:192
	s_waitcnt lgkmcnt(0)
	v_mfma_f32_16x16x32_bf16 v[70:73], v[174:177], v[142:145], v[70:73]
	ds_read_b128 v[174:177], v157
	s_waitcnt lgkmcnt(0)
	v_mfma_f32_16x16x32_bf16 v[66:69], v[174:177], v[130:133], v[66:69]
	ds_read_b128 v[130:133], v157 offset:64
	s_waitcnt lgkmcnt(0)
	v_mfma_f32_16x16x32_bf16 v[66:69], v[130:133], v[134:137], v[66:69]
	ds_read_b128 v[130:133], v157 offset:128
	s_waitcnt lgkmcnt(0)
	v_mfma_f32_16x16x32_bf16 v[66:69], v[130:133], v[138:141], v[66:69]
	ds_read_b128 v[130:133], v157 offset:192
	s_waitcnt lgkmcnt(0)
	v_mfma_f32_16x16x32_bf16 v[66:69], v[130:133], v[142:145], v[66:69]
	global_load_dwordx4 v[130:133], v[202:203], off offset:256
	global_load_dwordx4 v[134:137], v[202:203], off offset:320
	global_load_dwordx4 v[138:141], v[202:203], off offset:384
	global_load_dwordx4 v[142:145], v[202:203], off offset:448
	s_waitcnt vmcnt(3)
	v_lshlrev_b32_e32 v174, 16, v130
	v_and_b32_e32 v175, 0xffff0000, v130
	v_pk_mul_f32 v[174:175], v[146:147], v[174:175] op_sel_hi:[0,1]
	v_cvt_pk_bf16_f32 v130, v174, v175
	v_lshlrev_b32_e32 v174, 16, v131
	v_and_b32_e32 v175, 0xffff0000, v131
	v_pk_mul_f32 v[174:175], v[146:147], v[174:175] op_sel_hi:[0,1]
	v_cvt_pk_bf16_f32 v131, v174, v175
	v_lshlrev_b32_e32 v174, 16, v132
	v_and_b32_e32 v175, 0xffff0000, v132
	v_pk_mul_f32 v[174:175], v[146:147], v[174:175] op_sel_hi:[0,1]
	v_cvt_pk_bf16_f32 v132, v174, v175
	v_lshlrev_b32_e32 v174, 16, v133
	v_and_b32_e32 v175, 0xffff0000, v133
	v_pk_mul_f32 v[174:175], v[146:147], v[174:175] op_sel_hi:[0,1]
	v_cvt_pk_bf16_f32 v133, v174, v175
	s_waitcnt vmcnt(2)
	v_lshlrev_b32_e32 v174, 16, v134
	v_and_b32_e32 v175, 0xffff0000, v134
	v_pk_mul_f32 v[174:175], v[146:147], v[174:175] op_sel_hi:[0,1]
	v_cvt_pk_bf16_f32 v134, v174, v175
	v_lshlrev_b32_e32 v174, 16, v135
	v_and_b32_e32 v175, 0xffff0000, v135
	v_pk_mul_f32 v[174:175], v[146:147], v[174:175] op_sel_hi:[0,1]
	v_cvt_pk_bf16_f32 v135, v174, v175
	v_lshlrev_b32_e32 v174, 16, v136
	v_and_b32_e32 v175, 0xffff0000, v136
	v_pk_mul_f32 v[174:175], v[146:147], v[174:175] op_sel_hi:[0,1]
	v_cvt_pk_bf16_f32 v136, v174, v175
	v_lshlrev_b32_e32 v174, 16, v137
	v_and_b32_e32 v175, 0xffff0000, v137
	v_pk_mul_f32 v[174:175], v[146:147], v[174:175] op_sel_hi:[0,1]
	v_cvt_pk_bf16_f32 v137, v174, v175
	s_waitcnt vmcnt(1)
	v_lshlrev_b32_e32 v174, 16, v138
	v_and_b32_e32 v175, 0xffff0000, v138
	v_pk_mul_f32 v[174:175], v[146:147], v[174:175] op_sel_hi:[0,1]
	v_cvt_pk_bf16_f32 v138, v174, v175
	v_lshlrev_b32_e32 v174, 16, v139
	v_and_b32_e32 v175, 0xffff0000, v139
	v_pk_mul_f32 v[174:175], v[146:147], v[174:175] op_sel_hi:[0,1]
	v_cvt_pk_bf16_f32 v139, v174, v175
	v_lshlrev_b32_e32 v174, 16, v140
	v_and_b32_e32 v175, 0xffff0000, v140
	v_pk_mul_f32 v[174:175], v[146:147], v[174:175] op_sel_hi:[0,1]
	v_cvt_pk_bf16_f32 v140, v174, v175
	v_lshlrev_b32_e32 v174, 16, v141
	v_and_b32_e32 v175, 0xffff0000, v141
	v_pk_mul_f32 v[174:175], v[146:147], v[174:175] op_sel_hi:[0,1]
	v_cvt_pk_bf16_f32 v141, v174, v175
	s_waitcnt vmcnt(0)
	v_lshlrev_b32_e32 v174, 16, v142
	v_and_b32_e32 v175, 0xffff0000, v142
	v_pk_mul_f32 v[174:175], v[146:147], v[174:175] op_sel_hi:[0,1]
	v_cvt_pk_bf16_f32 v142, v174, v175
	v_lshlrev_b32_e32 v174, 16, v143
	v_and_b32_e32 v175, 0xffff0000, v143
	v_pk_mul_f32 v[174:175], v[146:147], v[174:175] op_sel_hi:[0,1]
	v_cvt_pk_bf16_f32 v143, v174, v175
	v_lshlrev_b32_e32 v174, 16, v144
	v_and_b32_e32 v175, 0xffff0000, v144
	v_pk_mul_f32 v[174:175], v[146:147], v[174:175] op_sel_hi:[0,1]
	v_cvt_pk_bf16_f32 v144, v174, v175
	v_lshlrev_b32_e32 v174, 16, v145
	v_and_b32_e32 v175, 0xffff0000, v145
	v_pk_mul_f32 v[174:175], v[146:147], v[174:175] op_sel_hi:[0,1]
	v_cvt_pk_bf16_f32 v145, v174, v175
	ds_read_b128 v[174:177], v156 offset:256
	s_waitcnt lgkmcnt(0)
; #define LAS __attribute__((address_space(3)))
; __device__ __forceinline__ f32x4 mfma16(bf16x8 a, bf16x8 b, f32x4 c) { return __builtin_amdgcn_mfma_f32_16x16x32_bf16(a, b, c, 0, 0, 0); }
; __device__ __forceinline__ void ret_out(const bf16* proj, const bf16* ST, bf16* mixed, const float* dexp, LAS unsigned char* lds, int vb, int nb, int tid_in0, int wave) {
;     ...
; #pragma unroll
;                     for (int v = 0; v < 16; ++v) {
;                         const LAS unsigned char* sp = Sx + (v * 16 + qi) * 528 + g * 16 + kh * 256;
; #pragma unroll
;                         for (int k4 = 0; k4 < 4; ++k4) o[v] = mfma16(*(const LAS bf16x8*)(sp + k4 * 64), qs[k4], o[v]);
;                         if ((v & 1) == 1) asm volatile("" ::: "memory");
;                     }
	v_mfma_f32_16x16x32_bf16 v[122:125], v[174:177], v[130:133], v[122:125]
	ds_read_b128 v[174:177], v156 offset:320
	v_add_u32_e32 v146, v148, v155
	s_waitcnt lgkmcnt(0)
	v_mfma_f32_16x16x32_bf16 v[122:125], v[174:177], v[134:137], v[122:125]
	ds_read_b128 v[174:177], v156 offset:384
	s_waitcnt lgkmcnt(0)
	v_mfma_f32_16x16x32_bf16 v[122:125], v[174:177], v[138:141], v[122:125]
	ds_read_b128 v[174:177], v156 offset:448
	s_waitcnt lgkmcnt(0)
	v_mfma_f32_16x16x32_bf16 v[122:125], v[174:177], v[142:145], v[122:125]
	ds_read_b128 v[174:177], v156 offset:8896
	ds_read_b128 v[178:181], v156 offset:8832
	ds_read_b128 v[232:235], v156 offset:8768
	ds_read_b128 v[236:239], v156 offset:8704
	s_waitcnt lgkmcnt(0)
	v_mfma_f32_16x16x32_bf16 v[126:129], v[236:239], v[130:133], v[126:129]
	v_mfma_f32_16x16x32_bf16 v[126:129], v[232:235], v[134:137], v[126:129]
	v_mfma_f32_16x16x32_bf16 v[126:129], v[178:181], v[138:141], v[126:129]
	v_mfma_f32_16x16x32_bf16 v[126:129], v[174:177], v[142:145], v[126:129]
	ds_read_b128 v[174:177], v156 offset:17152
	s_waitcnt lgkmcnt(0)
	v_mfma_f32_16x16x32_bf16 v[118:121], v[174:177], v[130:133], v[118:121]
	ds_read_b128 v[174:177], v156 offset:17216
	s_waitcnt lgkmcnt(0)
	v_mfma_f32_16x16x32_bf16 v[118:121], v[174:177], v[134:137], v[118:121]
	ds_read_b128 v[174:177], v156 offset:17280
	s_waitcnt lgkmcnt(0)
	v_mfma_f32_16x16x32_bf16 v[118:121], v[174:177], v[138:141], v[118:121]
	ds_read_b128 v[174:177], v156 offset:17344
	s_waitcnt lgkmcnt(0)
	v_mfma_f32_16x16x32_bf16 v[118:121], v[174:177], v[142:145], v[118:121]
	ds_read_b128 v[174:177], v156 offset:25792
	ds_read_b128 v[178:181], v156 offset:25728
	ds_read_b128 v[232:235], v156 offset:25664
	ds_read_b128 v[236:239], v156 offset:25600
	s_waitcnt lgkmcnt(0)
	v_mfma_f32_16x16x32_bf16 v[114:117], v[236:239], v[130:133], v[114:117]
	v_mfma_f32_16x16x32_bf16 v[114:117], v[232:235], v[134:137], v[114:117]
	v_mfma_f32_16x16x32_bf16 v[114:117], v[178:181], v[138:141], v[114:117]
	v_mfma_f32_16x16x32_bf16 v[114:117], v[174:177], v[142:145], v[114:117]
	ds_read_b128 v[174:177], v156 offset:34048
	s_waitcnt lgkmcnt(0)
	v_mfma_f32_16x16x32_bf16 v[110:113], v[174:177], v[130:133], v[110:113]
	ds_read_b128 v[174:177], v156 offset:34112
	s_waitcnt lgkmcnt(0)
	v_mfma_f32_16x16x32_bf16 v[110:113], v[174:177], v[134:137], v[110:113]
	ds_read_b128 v[174:177], v156 offset:34176
	s_waitcnt lgkmcnt(0)
	v_mfma_f32_16x16x32_bf16 v[110:113], v[174:177], v[138:141], v[110:113]
	ds_read_b128 v[174:177], v156 offset:34240
	s_waitcnt lgkmcnt(0)
	v_mfma_f32_16x16x32_bf16 v[110:113], v[174:177], v[142:145], v[110:113]
	ds_read_b128 v[174:177], v156 offset:42688
	ds_read_b128 v[178:181], v156 offset:42624
	ds_read_b128 v[232:235], v156 offset:42560
	ds_read_b128 v[236:239], v156 offset:42496
	s_waitcnt lgkmcnt(0)
	v_mfma_f32_16x16x32_bf16 v[106:109], v[236:239], v[130:133], v[106:109]
	v_mfma_f32_16x16x32_bf16 v[106:109], v[232:235], v[134:137], v[106:109]
	v_mfma_f32_16x16x32_bf16 v[106:109], v[178:181], v[138:141], v[106:109]
	v_mfma_f32_16x16x32_bf16 v[106:109], v[174:177], v[142:145], v[106:109]
	ds_read_b128 v[174:177], v156 offset:50944
	s_waitcnt lgkmcnt(0)
	v_mfma_f32_16x16x32_bf16 v[102:105], v[174:177], v[130:133], v[102:105]
	ds_read_b128 v[174:177], v156 offset:51008
	s_waitcnt lgkmcnt(0)
	v_mfma_f32_16x16x32_bf16 v[102:105], v[174:177], v[134:137], v[102:105]
	ds_read_b128 v[174:177], v156 offset:51072
	s_waitcnt lgkmcnt(0)
	v_mfma_f32_16x16x32_bf16 v[102:105], v[174:177], v[138:141], v[102:105]
	ds_read_b128 v[174:177], v156 offset:51136
	s_waitcnt lgkmcnt(0)
	v_mfma_f32_16x16x32_bf16 v[102:105], v[174:177], v[142:145], v[102:105]
	ds_read_b128 v[174:177], v156 offset:59584
	ds_read_b128 v[178:181], v156 offset:59520
	ds_read_b128 v[232:235], v156 offset:59456
	ds_read_b128 v[236:239], v156 offset:59392
	s_waitcnt lgkmcnt(0)
	v_mfma_f32_16x16x32_bf16 v[98:101], v[236:239], v[130:133], v[98:101]
	v_mfma_f32_16x16x32_bf16 v[98:101], v[232:235], v[134:137], v[98:101]
	v_mfma_f32_16x16x32_bf16 v[98:101], v[178:181], v[138:141], v[98:101]
	v_mfma_f32_16x16x32_bf16 v[98:101], v[174:177], v[142:145], v[98:101]
	ds_read_b128 v[174:177], v146
	s_waitcnt lgkmcnt(0)
; #define LAS __attribute__((address_space(3)))
; __device__ __forceinline__ f32x4 mfma16(bf16x8 a, bf16x8 b, f32x4 c) { return __builtin_amdgcn_mfma_f32_16x16x32_bf16(a, b, c, 0, 0, 0); }
; __device__ __forceinline__ void ret_out(const bf16* proj, const bf16* ST, bf16* mixed, const float* dexp, LAS unsigned char* lds, int vb, int nb, int tid_in0, int wave) {
;     ...
; #pragma unroll
;                     for (int v = 0; v < 16; ++v) {
;                         const LAS unsigned char* sp = Sx + (v * 16 + qi) * 528 + g * 16 + kh * 256;
; #pragma unroll
;                         for (int k4 = 0; k4 < 4; ++k4) o[v] = mfma16(*(const LAS bf16x8*)(sp + k4 * 64), qs[k4], o[v]);
;                         if ((v & 1) == 1) asm volatile("" ::: "memory");
;                     }
	v_mfma_f32_16x16x32_bf16 v[94:97], v[174:177], v[130:133], v[94:97]
	ds_read_b128 v[174:177], v146 offset:64
	s_waitcnt lgkmcnt(0)
	v_mfma_f32_16x16x32_bf16 v[94:97], v[174:177], v[134:137], v[94:97]
	ds_read_b128 v[174:177], v146 offset:128
	s_waitcnt lgkmcnt(0)
	v_mfma_f32_16x16x32_bf16 v[94:97], v[174:177], v[138:141], v[94:97]
	ds_read_b128 v[174:177], v146 offset:192
	v_add_u32_e32 v146, v148, v154
	s_waitcnt lgkmcnt(0)
	v_mfma_f32_16x16x32_bf16 v[94:97], v[174:177], v[142:145], v[94:97]
	ds_read_b128 v[174:177], v146 offset:192
	ds_read_b128 v[178:181], v146 offset:128
	ds_read_b128 v[232:235], v146 offset:64
	ds_read_b128 v[236:239], v146
	v_add_u32_e32 v146, v148, v153
	s_waitcnt lgkmcnt(0)
	v_mfma_f32_16x16x32_bf16 v[90:93], v[236:239], v[130:133], v[90:93]
	v_mfma_f32_16x16x32_bf16 v[90:93], v[232:235], v[134:137], v[90:93]
	v_mfma_f32_16x16x32_bf16 v[90:93], v[178:181], v[138:141], v[90:93]
	v_mfma_f32_16x16x32_bf16 v[90:93], v[174:177], v[142:145], v[90:93]
	ds_read_b128 v[174:177], v146
	s_waitcnt lgkmcnt(0)
	v_mfma_f32_16x16x32_bf16 v[86:89], v[174:177], v[130:133], v[86:89]
	ds_read_b128 v[174:177], v146 offset:64
	s_waitcnt lgkmcnt(0)
	v_mfma_f32_16x16x32_bf16 v[86:89], v[174:177], v[134:137], v[86:89]
	ds_read_b128 v[174:177], v146 offset:128
	s_waitcnt lgkmcnt(0)
	v_mfma_f32_16x16x32_bf16 v[86:89], v[174:177], v[138:141], v[86:89]
	ds_read_b128 v[174:177], v146 offset:192
	v_add_u32_e32 v146, v148, v152
	s_waitcnt lgkmcnt(0)
	v_mfma_f32_16x16x32_bf16 v[86:89], v[174:177], v[142:145], v[86:89]
	ds_read_b128 v[174:177], v146 offset:192
	ds_read_b128 v[178:181], v146 offset:128
	ds_read_b128 v[232:235], v146 offset:64
	ds_read_b128 v[236:239], v146
	v_add_u32_e32 v146, v148, v151
	s_waitcnt lgkmcnt(0)
	v_mfma_f32_16x16x32_bf16 v[82:85], v[236:239], v[130:133], v[82:85]
	v_mfma_f32_16x16x32_bf16 v[82:85], v[232:235], v[134:137], v[82:85]
	v_mfma_f32_16x16x32_bf16 v[82:85], v[178:181], v[138:141], v[82:85]
	v_mfma_f32_16x16x32_bf16 v[82:85], v[174:177], v[142:145], v[82:85]
	ds_read_b128 v[174:177], v146
	s_waitcnt lgkmcnt(0)
	v_mfma_f32_16x16x32_bf16 v[78:81], v[174:177], v[130:133], v[78:81]
	ds_read_b128 v[174:177], v146 offset:64
	s_waitcnt lgkmcnt(0)
	v_mfma_f32_16x16x32_bf16 v[78:81], v[174:177], v[134:137], v[78:81]
	ds_read_b128 v[174:177], v146 offset:128
	s_waitcnt lgkmcnt(0)
	v_mfma_f32_16x16x32_bf16 v[78:81], v[174:177], v[138:141], v[78:81]
	ds_read_b128 v[174:177], v146 offset:192
	v_add_u32_e32 v146, v148, v150
	s_waitcnt lgkmcnt(0)
	v_mfma_f32_16x16x32_bf16 v[78:81], v[174:177], v[142:145], v[78:81]
	ds_read_b128 v[174:177], v146 offset:192
	ds_read_b128 v[178:181], v146 offset:128
	ds_read_b128 v[232:235], v146 offset:64
	ds_read_b128 v[236:239], v146
	v_add_u32_e32 v146, v148, v149
	s_waitcnt lgkmcnt(0)
	v_mfma_f32_16x16x32_bf16 v[74:77], v[236:239], v[130:133], v[74:77]
	v_mfma_f32_16x16x32_bf16 v[74:77], v[232:235], v[134:137], v[74:77]
	v_mfma_f32_16x16x32_bf16 v[74:77], v[178:181], v[138:141], v[74:77]
	v_mfma_f32_16x16x32_bf16 v[74:77], v[174:177], v[142:145], v[74:77]
	ds_read_b128 v[174:177], v146
	s_waitcnt lgkmcnt(0)
	v_mfma_f32_16x16x32_bf16 v[70:73], v[174:177], v[130:133], v[70:73]
	ds_read_b128 v[174:177], v146 offset:64
	s_waitcnt lgkmcnt(0)
	v_mfma_f32_16x16x32_bf16 v[70:73], v[174:177], v[134:137], v[70:73]
	ds_read_b128 v[174:177], v146 offset:128
	s_waitcnt lgkmcnt(0)
	v_mfma_f32_16x16x32_bf16 v[70:73], v[174:177], v[138:141], v[70:73]
	ds_read_b128 v[174:177], v146 offset:192
	v_add_u32_e32 v146, v148, v147
	s_waitcnt lgkmcnt(0)
	v_mfma_f32_16x16x32_bf16 v[70:73], v[174:177], v[142:145], v[70:73]
	ds_read_b128 v[174:177], v146 offset:192
	ds_read_b128 v[178:181], v146 offset:128
	ds_read_b128 v[232:235], v146 offset:64
	ds_read_b128 v[236:239], v146
	s_waitcnt lgkmcnt(0)
	v_mfma_f32_16x16x32_bf16 v[66:69], v[236:239], v[130:133], v[66:69]
	v_mfma_f32_16x16x32_bf16 v[66:69], v[232:235], v[134:137], v[66:69]
	v_mfma_f32_16x16x32_bf16 v[66:69], v[178:181], v[138:141], v[66:69]
	v_mfma_f32_16x16x32_bf16 v[66:69], v[174:177], v[142:145], v[66:69]

; __device__ __forceinline__ unsigned pk2(float lo, float hi) { const f32x2 v = {lo, hi}; return __builtin_bit_cast(unsigned, __builtin_convertvector(v, bf16x2_t)); }
; __device__ __forceinline__ void ret_out(const bf16* proj, const bf16* ST, bf16* mixed, const float* dexp, LAS unsigned char* lds, int vb, int nb, int tid_in0, int wave) {
;     ...
;             else { const int un = unit + nb;
;                 if (un < 1536) { const int gc2 = un >> 3, h2 = un & 7, rowb2 = gc2 * 128;
; #pragma unroll
;                     for (int i = 0; i < 8; ++i) { const int id = tid + 512 * i, j = id >> 5, ch = id & 31;
;                         pf[i] = *(const v4u*)(proj + (size_t)(rowb2 + j) * NIN + C_RK + h2 * 256 + ch * 8); pf[8 + i] = *(const v4u*)(proj + (size_t)(rowb2 + j) * NIN + C_RV + h2 * 256 + ch * 8); } } }
;             if (have) {
;                 const float xi = dir == 0 ? __expf(lgf * (float)(iq + 1)) : __expf(lgb * (float)(128 - iq));
; #pragma unroll
;                 for (int kh = 0; kh < 2; ++kh) {
;                     bf16x8 qs[4];
; #pragma unroll
;                     for (int k4 = 0; k4 < 4; ++k4) { const int ks = 4 * kh + k4; const v4u q = *(const v4u*)(proj + (size_t)qrow * NIN + C_RQ + h * 256 + ks * 32 + g * 8); v4u r;
;                         r.x = pk2(bflo(q.x) * xi, bfhi(q.x) * xi); r.y = pk2(bflo(q.y) * xi, bfhi(q.y) * xi); r.z = pk2(bflo(q.z) * xi, bfhi(q.z) * xi); r.w = pk2(bflo(q.w) * xi, bfhi(q.w) * xi);
;                         qs[k4] = __builtin_bit_cast(bf16x8, r); }
.LBB0_848:
	s_and_b64 vcc, exec, s[4:5]
	s_lshl_b32 s4, s66, 8
	s_cbranch_vccnz .LBB0_833
	v_sub_u32_e32 v130, 0x80, v189
	v_cvt_f32_i32_e32 v130, v130
	v_mul_f32_e32 v130, v230, v130
	v_mul_f32_e32 v130, 0x3fb8aa3b, v130
	v_exp_f32_e32 v146, v130
	global_load_dwordx4 v[130:133], v[202:203], off
	global_load_dwordx4 v[134:137], v[202:203], off offset:64
	global_load_dwordx4 v[138:141], v[202:203], off offset:128
	global_load_dwordx4 v[142:145], v[202:203], off offset:192
	s_waitcnt vmcnt(3)
	v_lshlrev_b32_e32 v166, 16, v130
	v_and_b32_e32 v167, 0xffff0000, v130
	v_pk_mul_f32 v[166:167], v[146:147], v[166:167] op_sel_hi:[0,1]
	v_cvt_pk_bf16_f32 v130, v166, v167
	v_lshlrev_b32_e32 v166, 16, v131
	v_and_b32_e32 v167, 0xffff0000, v131
	v_pk_mul_f32 v[166:167], v[146:147], v[166:167] op_sel_hi:[0,1]
	v_cvt_pk_bf16_f32 v131, v166, v167
	v_lshlrev_b32_e32 v166, 16, v132
	v_and_b32_e32 v167, 0xffff0000, v132
	v_pk_mul_f32 v[166:167], v[146:147], v[166:167] op_sel_hi:[0,1]
	v_cvt_pk_bf16_f32 v132, v166, v167
	v_lshlrev_b32_e32 v166, 16, v133
	v_and_b32_e32 v167, 0xffff0000, v133
	v_pk_mul_f32 v[166:167], v[146:147], v[166:167] op_sel_hi:[0,1]
	v_cvt_pk_bf16_f32 v133, v166, v167
	s_waitcnt vmcnt(2)
	v_lshlrev_b32_e32 v166, 16, v134
	v_and_b32_e32 v167, 0xffff0000, v134
	v_pk_mul_f32 v[166:167], v[146:147], v[166:167] op_sel_hi:[0,1]
	v_cvt_pk_bf16_f32 v134, v166, v167
	v_lshlrev_b32_e32 v166, 16, v135
	v_and_b32_e32 v167, 0xffff0000, v135
	v_pk_mul_f32 v[166:167], v[146:147], v[166:167] op_sel_hi:[0,1]
	v_cvt_pk_bf16_f32 v135, v166, v167
	v_lshlrev_b32_e32 v166, 16, v136
	v_and_b32_e32 v167, 0xffff0000, v136
	v_pk_mul_f32 v[166:167], v[146:147], v[166:167] op_sel_hi:[0,1]
	v_cvt_pk_bf16_f32 v136, v166, v167
	v_lshlrev_b32_e32 v166, 16, v137
	v_and_b32_e32 v167, 0xffff0000, v137
	v_pk_mul_f32 v[166:167], v[146:147], v[166:167] op_sel_hi:[0,1]
	v_cvt_pk_bf16_f32 v137, v166, v167
	s_waitcnt vmcnt(1)
	v_lshlrev_b32_e32 v166, 16, v138
	v_and_b32_e32 v167, 0xffff0000, v138
	v_pk_mul_f32 v[166:167], v[146:147], v[166:167] op_sel_hi:[0,1]
	v_cvt_pk_bf16_f32 v138, v166, v167
	v_lshlrev_b32_e32 v166, 16, v139
	v_and_b32_e32 v167, 0xffff0000, v139
	v_pk_mul_f32 v[166:167], v[146:147], v[166:167] op_sel_hi:[0,1]
	v_cvt_pk_bf16_f32 v139, v166, v167
	v_lshlrev_b32_e32 v166, 16, v140
	v_and_b32_e32 v167, 0xffff0000, v140
	v_pk_mul_f32 v[166:167], v[146:147], v[166:167] op_sel_hi:[0,1]
	v_cvt_pk_bf16_f32 v140, v166, v167
	v_lshlrev_b32_e32 v166, 16, v141
	v_and_b32_e32 v167, 0xffff0000, v141
	v_pk_mul_f32 v[166:167], v[146:147], v[166:167] op_sel_hi:[0,1]
	v_cvt_pk_bf16_f32 v141, v166, v167
	s_waitcnt vmcnt(0)
	v_lshlrev_b32_e32 v166, 16, v142
	v_and_b32_e32 v167, 0xffff0000, v142
	v_pk_mul_f32 v[166:167], v[146:147], v[166:167] op_sel_hi:[0,1]
	v_cvt_pk_bf16_f32 v142, v166, v167
	v_lshlrev_b32_e32 v166, 16, v143
	v_and_b32_e32 v167, 0xffff0000, v143
	v_pk_mul_f32 v[166:167], v[146:147], v[166:167] op_sel_hi:[0,1]
	v_cvt_pk_bf16_f32 v143, v166, v167
	v_lshlrev_b32_e32 v166, 16, v144
	v_and_b32_e32 v167, 0xffff0000, v144
	v_pk_mul_f32 v[166:167], v[146:147], v[166:167] op_sel_hi:[0,1]
	v_cvt_pk_bf16_f32 v144, v166, v167
	v_lshlrev_b32_e32 v166, 16, v145
	v_and_b32_e32 v167, 0xffff0000, v145
	v_pk_mul_f32 v[166:167], v[146:147], v[166:167] op_sel_hi:[0,1]
	v_cvt_pk_bf16_f32 v145, v166, v167
	s_and_b64 vcc, exec, s[6:7]
	s_cbranch_vccnz .Lro_nopf_d1
	s_and_b32 s15, s64, 0xffffff80
	s_and_b32 s28, s11, 0x700
	s_waitcnt vmcnt(15)
	v_add_u32_e32 v2, s15, v208
	s_waitcnt vmcnt(8)
	v_mov_b64_e32 v[46:47], s[36:37]
	v_mad_i64_i32 v[2:3], s[26:27], v2, s33, v[46:47]
	s_lshl_b32 s62, s28, 1
	v_lshlrev_b64 v[48:49], 1, v[182:183]
	v_lshl_add_u64 v[2:3], v[2:3], 0, s[62:63]
	v_lshl_add_u64 v[2:3], v[2:3], 0, v[48:49]
	v_add_co_u32_e32 v4, vcc, 0x4000, v2
	s_waitcnt vmcnt(0)
	v_add_u32_e32 v62, s15, v190
	v_addc_co_u32_e32 v5, vcc, 0, v3, vcc
	v_add_co_u32_e32 v6, vcc, 0x5000, v2
	s_nop 1
	v_addc_co_u32_e32 v7, vcc, 0, v3, vcc
	global_load_dwordx4 v[2:5], v[4:5], off
	s_nop 0
	global_load_dwordx4 v[18:21], v[6:7], off
	v_add_u32_e32 v6, s15, v207
	v_mad_i64_i32 v[6:7], s[26:27], v6, s33, v[46:47]
	v_lshl_add_u64 v[6:7], v[6:7], 0, s[62:63]
	v_lshl_add_u64 v[6:7], v[6:7], 0, v[48:49]
	v_add_co_u32_e32 v8, vcc, 0x4000, v6
	s_nop 1
	v_addc_co_u32_e32 v9, vcc, 0, v7, vcc
	v_add_co_u32_e32 v10, vcc, 0x5000, v6
	s_nop 1
	v_addc_co_u32_e32 v11, vcc, 0, v7, vcc
	global_load_dwordx4 v[6:9], v[8:9], off
	s_nop 0
	global_load_dwordx4 v[22:25], v[10:11], off
	v_add_u32_e32 v10, s15, v206
	v_mad_i64_i32 v[10:11], s[26:27], v10, s33, v[46:47]
	v_lshl_add_u64 v[10:11], v[10:11], 0, s[62:63]
	v_lshl_add_u64 v[10:11], v[10:11], 0, v[48:49]
	v_add_co_u32_e32 v12, vcc, 0x4000, v10
	s_nop 1
	v_addc_co_u32_e32 v13, vcc, 0, v11, vcc
	v_add_co_u32_e32 v14, vcc, 0x5000, v10
	s_nop 1
	v_addc_co_u32_e32 v15, vcc, 0, v11, vcc
	global_load_dwordx4 v[10:13], v[12:13], off
	s_nop 0
	global_load_dwordx4 v[34:37], v[14:15], off
	v_add_u32_e32 v14, s15, v205
	v_mad_i64_i32 v[14:15], s[26:27], v14, s33, v[46:47]
	v_lshl_add_u64 v[14:15], v[14:15], 0, s[62:63]
	v_lshl_add_u64 v[14:15], v[14:15], 0, v[48:49]
	v_add_co_u32_e32 v16, vcc, 0x4000, v14
	s_nop 1
	v_addc_co_u32_e32 v17, vcc, 0, v15, vcc
	v_add_co_u32_e32 v26, vcc, 0x5000, v14
	s_nop 1
	v_addc_co_u32_e32 v27, vcc, 0, v15, vcc
	global_load_dwordx4 v[14:17], v[16:17], off
	s_nop 0
	global_load_dwordx4 v[38:41], v[26:27], off
	v_add_u32_e32 v26, s15, v204
	v_mad_i64_i32 v[26:27], s[26:27], v26, s33, v[46:47]
	v_lshl_add_u64 v[26:27], v[26:27], 0, s[62:63]
	v_lshl_add_u64 v[26:27], v[26:27], 0, v[48:49]
	v_add_co_u32_e32 v28, vcc, 0x4000, v26
	s_nop 1
; #define LAS __attribute__((address_space(3)))
; __device__ __forceinline__ unsigned pk2(float lo, float hi) { const f32x2 v = {lo, hi}; return __builtin_bit_cast(unsigned, __builtin_convertvector(v, bf16x2_t)); }
; __device__ __forceinline__ f32x4 mfma16(bf16x8 a, bf16x8 b, f32x4 c) { return __builtin_amdgcn_mfma_f32_16x16x32_bf16(a, b, c, 0, 0, 0); }
; __device__ __forceinline__ void ret_out(const bf16* proj, const bf16* ST, bf16* mixed, const float* dexp, LAS unsigned char* lds, int vb, int nb, int tid_in0, int wave) {
;     ...
;                 if (un < 1536) { const int gc2 = un >> 3, h2 = un & 7, rowb2 = gc2 * 128;
; #pragma unroll
;                     for (int i = 0; i < 8; ++i) { const int id = tid + 512 * i, j = id >> 5, ch = id & 31;
;                         pf[i] = *(const v4u*)(proj + (size_t)(rowb2 + j) * NIN + C_RK + h2 * 256 + ch * 8); pf[8 + i] = *(const v4u*)(proj + (size_t)(rowb2 + j) * NIN + C_RV + h2 * 256 + ch * 8); } } }
;             if (have) {
;                 const float xi = dir == 0 ? __expf(lgf * (float)(iq + 1)) : __expf(lgb * (float)(128 - iq));
; #pragma unroll
;                 for (int kh = 0; kh < 2; ++kh) {
;                     bf16x8 qs[4];
; #pragma unroll
;                     for (int k4 = 0; k4 < 4; ++k4) { const int ks = 4 * kh + k4; const v4u q = *(const v4u*)(proj + (size_t)qrow * NIN + C_RQ + h * 256 + ks * 32 + g * 8); v4u r;
;                         r.x = pk2(bflo(q.x) * xi, bfhi(q.x) * xi); r.y = pk2(bflo(q.y) * xi, bfhi(q.y) * xi); r.z = pk2(bflo(q.z) * xi, bfhi(q.z) * xi); r.w = pk2(bflo(q.w) * xi, bfhi(q.w) * xi);
;                         qs[k4] = __builtin_bit_cast(bf16x8, r); }
; #pragma unroll
;                     for (int v = 0; v < 16; ++v) {
;                         const LAS unsigned char* sp = Sx + (v * 16 + qi) * 528 + g * 16 + kh * 256;
; #pragma unroll
;                         for (int k4 = 0; k4 < 4; ++k4) o[v] = mfma16(*(const LAS bf16x8*)(sp + k4 * 64), qs[k4], o[v]);
;                         if ((v & 1) == 1) asm volatile("" ::: "memory");
	v_addc_co_u32_e32 v29, vcc, 0, v27, vcc
	v_add_co_u32_e32 v30, vcc, 0x5000, v26
	s_nop 1
	v_addc_co_u32_e32 v31, vcc, 0, v27, vcc
	global_load_dwordx4 v[26:29], v[28:29], off
	s_nop 0
	global_load_dwordx4 v[50:53], v[30:31], off
	v_add_u32_e32 v30, s15, v199
	v_mad_i64_i32 v[30:31], s[26:27], v30, s33, v[46:47]
	v_lshl_add_u64 v[30:31], v[30:31], 0, s[62:63]
	v_lshl_add_u64 v[30:31], v[30:31], 0, v[48:49]
	v_add_co_u32_e32 v32, vcc, 0x4000, v30
	s_nop 1
	v_addc_co_u32_e32 v33, vcc, 0, v31, vcc
	v_add_co_u32_e32 v42, vcc, 0x5000, v30
	s_nop 1
	v_addc_co_u32_e32 v43, vcc, 0, v31, vcc
	global_load_dwordx4 v[30:33], v[32:33], off
	s_nop 0
	global_load_dwordx4 v[54:57], v[42:43], off
	v_add_u32_e32 v42, s15, v192
	v_mad_i64_i32 v[42:43], s[26:27], v42, s33, v[46:47]
	v_lshl_add_u64 v[42:43], v[42:43], 0, s[62:63]
	v_lshl_add_u64 v[42:43], v[42:43], 0, v[48:49]
	v_add_co_u32_e32 v44, vcc, 0x4000, v42
	v_mad_i64_i32 v[46:47], s[26:27], v62, s33, v[46:47]
	s_nop 0
	v_addc_co_u32_e32 v45, vcc, 0, v43, vcc
	v_add_co_u32_e32 v58, vcc, 0x5000, v42
	v_lshl_add_u64 v[46:47], v[46:47], 0, s[62:63]
	s_nop 0
	v_addc_co_u32_e32 v59, vcc, 0, v43, vcc
	v_lshl_add_u64 v[46:47], v[46:47], 0, v[48:49]
	v_add_co_u32_e32 v48, vcc, 0x4000, v46
	global_load_dwordx4 v[42:45], v[44:45], off
	s_nop 0
	global_load_dwordx4 v[58:61], v[58:59], off
	v_addc_co_u32_e32 v49, vcc, 0, v47, vcc
	v_add_co_u32_e32 v62, vcc, 0x5000, v46
	s_nop 1
	v_addc_co_u32_e32 v63, vcc, 0, v47, vcc
	global_load_dwordx4 v[46:49], v[48:49], off
	s_nop 0
	global_load_dwordx4 v[62:65], v[62:63], off
.Lro_nopf_d1:
	ds_read_b128 v[166:169], v156
	s_waitcnt lgkmcnt(0)
	v_mfma_f32_16x16x32_bf16 v[122:125], v[166:169], v[130:133], v[122:125]
	ds_read_b128 v[166:169], v156 offset:64
	s_waitcnt lgkmcnt(0)
	v_mfma_f32_16x16x32_bf16 v[122:125], v[166:169], v[134:137], v[122:125]
	ds_read_b128 v[166:169], v156 offset:128
	s_waitcnt lgkmcnt(0)
	v_mfma_f32_16x16x32_bf16 v[122:125], v[166:169], v[138:141], v[122:125]
	ds_read_b128 v[166:169], v156 offset:192
	s_waitcnt lgkmcnt(0)
	v_mfma_f32_16x16x32_bf16 v[122:125], v[166:169], v[142:145], v[122:125]
	ds_read_b128 v[166:169], v156 offset:8640
	ds_read_b128 v[170:173], v156 offset:8576
	ds_read_b128 v[174:177], v156 offset:8512
	ds_read_b128 v[178:181], v156 offset:8448
	s_waitcnt lgkmcnt(0)
	v_mfma_f32_16x16x32_bf16 v[126:129], v[178:181], v[130:133], v[126:129]
	v_mfma_f32_16x16x32_bf16 v[126:129], v[174:177], v[134:137], v[126:129]
	v_mfma_f32_16x16x32_bf16 v[126:129], v[170:173], v[138:141], v[126:129]
	v_mfma_f32_16x16x32_bf16 v[126:129], v[166:169], v[142:145], v[126:129]
	ds_read_b128 v[166:169], v156 offset:16896
	s_waitcnt lgkmcnt(0)
	v_mfma_f32_16x16x32_bf16 v[118:121], v[166:169], v[130:133], v[118:121]
	ds_read_b128 v[166:169], v156 offset:16960
	s_waitcnt lgkmcnt(0)
	v_mfma_f32_16x16x32_bf16 v[118:121], v[166:169], v[134:137], v[118:121]
	ds_read_b128 v[166:169], v156 offset:17024
	s_waitcnt lgkmcnt(0)
	v_mfma_f32_16x16x32_bf16 v[118:121], v[166:169], v[138:141], v[118:121]
	ds_read_b128 v[166:169], v156 offset:17088
	s_waitcnt lgkmcnt(0)
	v_mfma_f32_16x16x32_bf16 v[118:121], v[166:169], v[142:145], v[118:121]
	ds_read_b128 v[166:169], v156 offset:25536
	ds_read_b128 v[170:173], v156 offset:25472
	ds_read_b128 v[174:177], v156 offset:25408
	ds_read_b128 v[178:181], v156 offset:25344
	s_waitcnt lgkmcnt(0)
	v_mfma_f32_16x16x32_bf16 v[114:117], v[178:181], v[130:133], v[114:117]
	v_mfma_f32_16x16x32_bf16 v[114:117], v[174:177], v[134:137], v[114:117]
	v_mfma_f32_16x16x32_bf16 v[114:117], v[170:173], v[138:141], v[114:117]
	v_mfma_f32_16x16x32_bf16 v[114:117], v[166:169], v[142:145], v[114:117]
	ds_read_b128 v[166:169], v156 offset:33792
	s_waitcnt lgkmcnt(0)
	v_mfma_f32_16x16x32_bf16 v[110:113], v[166:169], v[130:133], v[110:113]
	ds_read_b128 v[166:169], v156 offset:33856
	s_waitcnt lgkmcnt(0)
	v_mfma_f32_16x16x32_bf16 v[110:113], v[166:169], v[134:137], v[110:113]
	ds_read_b128 v[166:169], v156 offset:33920
	s_waitcnt lgkmcnt(0)
	v_mfma_f32_16x16x32_bf16 v[110:113], v[166:169], v[138:141], v[110:113]
	ds_read_b128 v[166:169], v156 offset:33984
	s_waitcnt lgkmcnt(0)
	v_mfma_f32_16x16x32_bf16 v[110:113], v[166:169], v[142:145], v[110:113]
	ds_read_b128 v[166:169], v156 offset:42432
	ds_read_b128 v[170:173], v156 offset:42368
	ds_read_b128 v[174:177], v156 offset:42304
	ds_read_b128 v[178:181], v156 offset:42240
	s_waitcnt lgkmcnt(0)
	v_mfma_f32_16x16x32_bf16 v[106:109], v[178:181], v[130:133], v[106:109]
	v_mfma_f32_16x16x32_bf16 v[106:109], v[174:177], v[134:137], v[106:109]
	v_mfma_f32_16x16x32_bf16 v[106:109], v[170:173], v[138:141], v[106:109]
	v_mfma_f32_16x16x32_bf16 v[106:109], v[166:169], v[142:145], v[106:109]
	ds_read_b128 v[166:169], v156 offset:50688
	s_waitcnt lgkmcnt(0)
	v_mfma_f32_16x16x32_bf16 v[102:105], v[166:169], v[130:133], v[102:105]
	ds_read_b128 v[166:169], v156 offset:50752
	s_waitcnt lgkmcnt(0)
	v_mfma_f32_16x16x32_bf16 v[102:105], v[166:169], v[134:137], v[102:105]
	ds_read_b128 v[166:169], v156 offset:50816
	s_waitcnt lgkmcnt(0)
	v_mfma_f32_16x16x32_bf16 v[102:105], v[166:169], v[138:141], v[102:105]
	ds_read_b128 v[166:169], v156 offset:50880
	s_waitcnt lgkmcnt(0)
	v_mfma_f32_16x16x32_bf16 v[102:105], v[166:169], v[142:145], v[102:105]
	ds_read_b128 v[166:169], v156 offset:59328
	ds_read_b128 v[170:173], v156 offset:59264
	ds_read_b128 v[174:177], v156 offset:59200
	ds_read_b128 v[178:181], v156 offset:59136
	s_waitcnt lgkmcnt(0)
	v_mfma_f32_16x16x32_bf16 v[98:101], v[178:181], v[130:133], v[98:101]
	v_mfma_f32_16x16x32_bf16 v[98:101], v[174:177], v[134:137], v[98:101]
	v_mfma_f32_16x16x32_bf16 v[98:101], v[170:173], v[138:141], v[98:101]
	v_mfma_f32_16x16x32_bf16 v[98:101], v[166:169], v[142:145], v[98:101]
	ds_read_b128 v[166:169], v164
	s_waitcnt lgkmcnt(0)
; #define LAS __attribute__((address_space(3)))
; __device__ __forceinline__ unsigned pk2(float lo, float hi) { const f32x2 v = {lo, hi}; return __builtin_bit_cast(unsigned, __builtin_convertvector(v, bf16x2_t)); }
; __device__ __forceinline__ f32x4 mfma16(bf16x8 a, bf16x8 b, f32x4 c) { return __builtin_amdgcn_mfma_f32_16x16x32_bf16(a, b, c, 0, 0, 0); }
; __device__ __forceinline__ void ret_out(const bf16* proj, const bf16* ST, bf16* mixed, const float* dexp, LAS unsigned char* lds, int vb, int nb, int tid_in0, int wave) {
;     ...
;                 for (int kh = 0; kh < 2; ++kh) {
;                     bf16x8 qs[4];
; #pragma unroll
;                     for (int k4 = 0; k4 < 4; ++k4) { const int ks = 4 * kh + k4; const v4u q = *(const v4u*)(proj + (size_t)qrow * NIN + C_RQ + h * 256 + ks * 32 + g * 8); v4u r;
;                         r.x = pk2(bflo(q.x) * xi, bfhi(q.x) * xi); r.y = pk2(bflo(q.y) * xi, bfhi(q.y) * xi); r.z = pk2(bflo(q.z) * xi, bfhi(q.z) * xi); r.w = pk2(bflo(q.w) * xi, bfhi(q.w) * xi);
;                         qs[k4] = __builtin_bit_cast(bf16x8, r); }
; #pragma unroll
;                     for (int v = 0; v < 16; ++v) {
;                         const LAS unsigned char* sp = Sx + (v * 16 + qi) * 528 + g * 16 + kh * 256;
; #pragma unroll
;                         for (int k4 = 0; k4 < 4; ++k4) o[v] = mfma16(*(const LAS bf16x8*)(sp + k4 * 64), qs[k4], o[v]);
;                         if ((v & 1) == 1) asm volatile("" ::: "memory");
;                     }
	v_mfma_f32_16x16x32_bf16 v[94:97], v[166:169], v[130:133], v[94:97]
	ds_read_b128 v[166:169], v164 offset:64
	s_waitcnt lgkmcnt(0)
	v_mfma_f32_16x16x32_bf16 v[94:97], v[166:169], v[134:137], v[94:97]
	ds_read_b128 v[166:169], v164 offset:128
	s_waitcnt lgkmcnt(0)
	v_mfma_f32_16x16x32_bf16 v[94:97], v[166:169], v[138:141], v[94:97]
	ds_read_b128 v[164:167], v164 offset:192
	s_waitcnt lgkmcnt(0)
	v_mfma_f32_16x16x32_bf16 v[94:97], v[164:167], v[142:145], v[94:97]
	ds_read_b128 v[164:167], v163
	s_waitcnt lgkmcnt(0)
	v_mfma_f32_16x16x32_bf16 v[90:93], v[164:167], v[130:133], v[90:93]
	ds_read_b128 v[164:167], v163 offset:64
	s_waitcnt lgkmcnt(0)
	v_mfma_f32_16x16x32_bf16 v[90:93], v[164:167], v[134:137], v[90:93]
	ds_read_b128 v[164:167], v163 offset:128
	s_waitcnt lgkmcnt(0)
	v_mfma_f32_16x16x32_bf16 v[90:93], v[164:167], v[138:141], v[90:93]
	ds_read_b128 v[164:167], v163 offset:192
	s_waitcnt lgkmcnt(0)
	v_mfma_f32_16x16x32_bf16 v[90:93], v[164:167], v[142:145], v[90:93]
	ds_read_b128 v[164:167], v162
	s_waitcnt lgkmcnt(0)
	v_mfma_f32_16x16x32_bf16 v[86:89], v[164:167], v[130:133], v[86:89]
	ds_read_b128 v[164:167], v162 offset:64
	s_waitcnt lgkmcnt(0)
	v_mfma_f32_16x16x32_bf16 v[86:89], v[164:167], v[134:137], v[86:89]
	ds_read_b128 v[164:167], v162 offset:128
	s_waitcnt lgkmcnt(0)
	v_mfma_f32_16x16x32_bf16 v[86:89], v[164:167], v[138:141], v[86:89]
	ds_read_b128 v[162:165], v162 offset:192
	s_waitcnt lgkmcnt(0)
	v_mfma_f32_16x16x32_bf16 v[86:89], v[162:165], v[142:145], v[86:89]
	ds_read_b128 v[162:165], v161
	s_waitcnt lgkmcnt(0)
	v_mfma_f32_16x16x32_bf16 v[82:85], v[162:165], v[130:133], v[82:85]
	ds_read_b128 v[162:165], v161 offset:64
	s_waitcnt lgkmcnt(0)
	v_mfma_f32_16x16x32_bf16 v[82:85], v[162:165], v[134:137], v[82:85]
	ds_read_b128 v[162:165], v161 offset:128
	s_waitcnt lgkmcnt(0)
	v_mfma_f32_16x16x32_bf16 v[82:85], v[162:165], v[138:141], v[82:85]
	ds_read_b128 v[162:165], v161 offset:192
	s_waitcnt lgkmcnt(0)
	v_mfma_f32_16x16x32_bf16 v[82:85], v[162:165], v[142:145], v[82:85]
	ds_read_b128 v[162:165], v160
	s_waitcnt lgkmcnt(0)
	v_mfma_f32_16x16x32_bf16 v[78:81], v[162:165], v[130:133], v[78:81]
	ds_read_b128 v[162:165], v160 offset:64
	s_waitcnt lgkmcnt(0)
	v_mfma_f32_16x16x32_bf16 v[78:81], v[162:165], v[134:137], v[78:81]
	ds_read_b128 v[162:165], v160 offset:128
	s_waitcnt lgkmcnt(0)
	v_mfma_f32_16x16x32_bf16 v[78:81], v[162:165], v[138:141], v[78:81]
	ds_read_b128 v[160:163], v160 offset:192
	s_waitcnt lgkmcnt(0)
	v_mfma_f32_16x16x32_bf16 v[78:81], v[160:163], v[142:145], v[78:81]
	ds_read_b128 v[160:163], v159
	s_waitcnt lgkmcnt(0)
	v_mfma_f32_16x16x32_bf16 v[74:77], v[160:163], v[130:133], v[74:77]
	ds_read_b128 v[160:163], v159 offset:64
	s_waitcnt lgkmcnt(0)
	v_mfma_f32_16x16x32_bf16 v[74:77], v[160:163], v[134:137], v[74:77]
	ds_read_b128 v[160:163], v159 offset:128
	s_waitcnt lgkmcnt(0)
	v_mfma_f32_16x16x32_bf16 v[74:77], v[160:163], v[138:141], v[74:77]
	ds_read_b128 v[160:163], v159 offset:192
	s_waitcnt lgkmcnt(0)
	v_mfma_f32_16x16x32_bf16 v[74:77], v[160:163], v[142:145], v[74:77]
	ds_read_b128 v[160:163], v158
	s_waitcnt lgkmcnt(0)
	v_mfma_f32_16x16x32_bf16 v[70:73], v[160:163], v[130:133], v[70:73]
	ds_read_b128 v[160:163], v158 offset:64
	s_waitcnt lgkmcnt(0)
	v_mfma_f32_16x16x32_bf16 v[70:73], v[160:163], v[134:137], v[70:73]
	ds_read_b128 v[160:163], v158 offset:128
	s_waitcnt lgkmcnt(0)
	v_mfma_f32_16x16x32_bf16 v[70:73], v[160:163], v[138:141], v[70:73]
	ds_read_b128 v[158:161], v158 offset:192
	s_waitcnt lgkmcnt(0)
	v_mfma_f32_16x16x32_bf16 v[70:73], v[158:161], v[142:145], v[70:73]
	ds_read_b128 v[158:161], v157
	s_waitcnt lgkmcnt(0)
	v_mfma_f32_16x16x32_bf16 v[66:69], v[158:161], v[130:133], v[66:69]
	ds_read_b128 v[130:133], v157 offset:64
	s_waitcnt lgkmcnt(0)
	v_mfma_f32_16x16x32_bf16 v[66:69], v[130:133], v[134:137], v[66:69]
	ds_read_b128 v[130:133], v157 offset:128
	s_waitcnt lgkmcnt(0)
	v_mfma_f32_16x16x32_bf16 v[66:69], v[130:133], v[138:141], v[66:69]
	ds_read_b128 v[130:133], v157 offset:192
	s_waitcnt lgkmcnt(0)
	v_mfma_f32_16x16x32_bf16 v[66:69], v[130:133], v[142:145], v[66:69]
	global_load_dwordx4 v[130:133], v[202:203], off offset:256
	global_load_dwordx4 v[134:137], v[202:203], off offset:320
	global_load_dwordx4 v[138:141], v[202:203], off offset:384
	global_load_dwordx4 v[142:145], v[202:203], off offset:448
	s_waitcnt vmcnt(3)
	v_lshlrev_b32_e32 v158, 16, v130
	v_and_b32_e32 v159, 0xffff0000, v130
	v_pk_mul_f32 v[158:159], v[146:147], v[158:159] op_sel_hi:[0,1]
	v_cvt_pk_bf16_f32 v130, v158, v159
	v_lshlrev_b32_e32 v158, 16, v131
	v_and_b32_e32 v159, 0xffff0000, v131
	v_pk_mul_f32 v[158:159], v[146:147], v[158:159] op_sel_hi:[0,1]
	v_cvt_pk_bf16_f32 v131, v158, v159
	v_lshlrev_b32_e32 v158, 16, v132
	v_and_b32_e32 v159, 0xffff0000, v132
	v_pk_mul_f32 v[158:159], v[146:147], v[158:159] op_sel_hi:[0,1]
	v_cvt_pk_bf16_f32 v132, v158, v159
	v_lshlrev_b32_e32 v158, 16, v133
	v_and_b32_e32 v159, 0xffff0000, v133
	v_pk_mul_f32 v[158:159], v[146:147], v[158:159] op_sel_hi:[0,1]
	v_cvt_pk_bf16_f32 v133, v158, v159
	s_waitcnt vmcnt(2)
	v_lshlrev_b32_e32 v158, 16, v134
	v_and_b32_e32 v159, 0xffff0000, v134
	v_pk_mul_f32 v[158:159], v[146:147], v[158:159] op_sel_hi:[0,1]
	v_cvt_pk_bf16_f32 v134, v158, v159
	v_lshlrev_b32_e32 v158, 16, v135
	v_and_b32_e32 v159, 0xffff0000, v135
	v_pk_mul_f32 v[158:159], v[146:147], v[158:159] op_sel_hi:[0,1]
	v_cvt_pk_bf16_f32 v135, v158, v159
	v_lshlrev_b32_e32 v158, 16, v136
	v_and_b32_e32 v159, 0xffff0000, v136
	v_pk_mul_f32 v[158:159], v[146:147], v[158:159] op_sel_hi:[0,1]
	v_cvt_pk_bf16_f32 v136, v158, v159
	v_lshlrev_b32_e32 v158, 16, v137
	v_and_b32_e32 v159, 0xffff0000, v137
	v_pk_mul_f32 v[158:159], v[146:147], v[158:159] op_sel_hi:[0,1]
	v_cvt_pk_bf16_f32 v137, v158, v159
	s_waitcnt vmcnt(1)
; #define LAS __attribute__((address_space(3)))
; __device__ __forceinline__ unsigned pk2(float lo, float hi) { const f32x2 v = {lo, hi}; return __builtin_bit_cast(unsigned, __builtin_convertvector(v, bf16x2_t)); }
; __device__ __forceinline__ f32x4 mfma16(bf16x8 a, bf16x8 b, f32x4 c) { return __builtin_amdgcn_mfma_f32_16x16x32_bf16(a, b, c, 0, 0, 0); }
; __device__ __forceinline__ void ret_out(const bf16* proj, const bf16* ST, bf16* mixed, const float* dexp, LAS unsigned char* lds, int vb, int nb, int tid_in0, int wave) {
;     ...
;                 for (int kh = 0; kh < 2; ++kh) {
;                     bf16x8 qs[4];
; #pragma unroll
;                     for (int k4 = 0; k4 < 4; ++k4) { const int ks = 4 * kh + k4; const v4u q = *(const v4u*)(proj + (size_t)qrow * NIN + C_RQ + h * 256 + ks * 32 + g * 8); v4u r;
;                         r.x = pk2(bflo(q.x) * xi, bfhi(q.x) * xi); r.y = pk2(bflo(q.y) * xi, bfhi(q.y) * xi); r.z = pk2(bflo(q.z) * xi, bfhi(q.z) * xi); r.w = pk2(bflo(q.w) * xi, bfhi(q.w) * xi);
;                         qs[k4] = __builtin_bit_cast(bf16x8, r); }
; #pragma unroll
;                     for (int v = 0; v < 16; ++v) {
;                         const LAS unsigned char* sp = Sx + (v * 16 + qi) * 528 + g * 16 + kh * 256;
; #pragma unroll
;                         for (int k4 = 0; k4 < 4; ++k4) o[v] = mfma16(*(const LAS bf16x8*)(sp + k4 * 64), qs[k4], o[v]);
;                         if ((v & 1) == 1) asm volatile("" ::: "memory");
;                     }
	v_lshlrev_b32_e32 v158, 16, v138
	v_and_b32_e32 v159, 0xffff0000, v138
	v_pk_mul_f32 v[158:159], v[146:147], v[158:159] op_sel_hi:[0,1]
	v_cvt_pk_bf16_f32 v138, v158, v159
	v_lshlrev_b32_e32 v158, 16, v139
	v_and_b32_e32 v159, 0xffff0000, v139
	v_pk_mul_f32 v[158:159], v[146:147], v[158:159] op_sel_hi:[0,1]
	v_cvt_pk_bf16_f32 v139, v158, v159
	v_lshlrev_b32_e32 v158, 16, v140
	v_and_b32_e32 v159, 0xffff0000, v140
	v_pk_mul_f32 v[158:159], v[146:147], v[158:159] op_sel_hi:[0,1]
	v_cvt_pk_bf16_f32 v140, v158, v159
	v_lshlrev_b32_e32 v158, 16, v141
	v_and_b32_e32 v159, 0xffff0000, v141
	v_pk_mul_f32 v[158:159], v[146:147], v[158:159] op_sel_hi:[0,1]
	v_cvt_pk_bf16_f32 v141, v158, v159
	s_waitcnt vmcnt(0)
	v_lshlrev_b32_e32 v158, 16, v142
	v_and_b32_e32 v159, 0xffff0000, v142
	v_pk_mul_f32 v[158:159], v[146:147], v[158:159] op_sel_hi:[0,1]
	v_cvt_pk_bf16_f32 v142, v158, v159
	v_lshlrev_b32_e32 v158, 16, v143
	v_and_b32_e32 v159, 0xffff0000, v143
	v_pk_mul_f32 v[158:159], v[146:147], v[158:159] op_sel_hi:[0,1]
	v_cvt_pk_bf16_f32 v143, v158, v159
	v_lshlrev_b32_e32 v158, 16, v144
	v_and_b32_e32 v159, 0xffff0000, v144
	v_pk_mul_f32 v[158:159], v[146:147], v[158:159] op_sel_hi:[0,1]
	v_cvt_pk_bf16_f32 v144, v158, v159
	v_lshlrev_b32_e32 v158, 16, v145
	v_and_b32_e32 v159, 0xffff0000, v145
	v_pk_mul_f32 v[158:159], v[146:147], v[158:159] op_sel_hi:[0,1]
	v_cvt_pk_bf16_f32 v145, v158, v159
	ds_read_b128 v[158:161], v156 offset:256
	s_waitcnt lgkmcnt(0)
	v_mfma_f32_16x16x32_bf16 v[122:125], v[158:161], v[130:133], v[122:125]
	ds_read_b128 v[158:161], v156 offset:320
	v_add_u32_e32 v146, v148, v155
	s_waitcnt lgkmcnt(0)
	v_mfma_f32_16x16x32_bf16 v[122:125], v[158:161], v[134:137], v[122:125]
	ds_read_b128 v[158:161], v156 offset:384
	s_waitcnt lgkmcnt(0)
	v_mfma_f32_16x16x32_bf16 v[122:125], v[158:161], v[138:141], v[122:125]
	ds_read_b128 v[158:161], v156 offset:448
	s_waitcnt lgkmcnt(0)
	v_mfma_f32_16x16x32_bf16 v[122:125], v[158:161], v[142:145], v[122:125]
	ds_read_b128 v[158:161], v156 offset:8896
	ds_read_b128 v[162:165], v156 offset:8832
	ds_read_b128 v[166:169], v156 offset:8768
	ds_read_b128 v[170:173], v156 offset:8704
	s_waitcnt lgkmcnt(0)
	v_mfma_f32_16x16x32_bf16 v[126:129], v[170:173], v[130:133], v[126:129]
	v_mfma_f32_16x16x32_bf16 v[126:129], v[166:169], v[134:137], v[126:129]
	v_mfma_f32_16x16x32_bf16 v[126:129], v[162:165], v[138:141], v[126:129]
	v_mfma_f32_16x16x32_bf16 v[126:129], v[158:161], v[142:145], v[126:129]
	ds_read_b128 v[158:161], v156 offset:17152
	s_waitcnt lgkmcnt(0)
	v_mfma_f32_16x16x32_bf16 v[118:121], v[158:161], v[130:133], v[118:121]
	ds_read_b128 v[158:161], v156 offset:17216
	s_waitcnt lgkmcnt(0)
	v_mfma_f32_16x16x32_bf16 v[118:121], v[158:161], v[134:137], v[118:121]
	ds_read_b128 v[158:161], v156 offset:17280
	s_waitcnt lgkmcnt(0)
	v_mfma_f32_16x16x32_bf16 v[118:121], v[158:161], v[138:141], v[118:121]
	ds_read_b128 v[158:161], v156 offset:17344
	s_waitcnt lgkmcnt(0)
	v_mfma_f32_16x16x32_bf16 v[118:121], v[158:161], v[142:145], v[118:121]
	ds_read_b128 v[158:161], v156 offset:25792
	ds_read_b128 v[162:165], v156 offset:25728
	ds_read_b128 v[166:169], v156 offset:25664
	ds_read_b128 v[170:173], v156 offset:25600
	s_waitcnt lgkmcnt(0)
	v_mfma_f32_16x16x32_bf16 v[114:117], v[170:173], v[130:133], v[114:117]
	v_mfma_f32_16x16x32_bf16 v[114:117], v[166:169], v[134:137], v[114:117]
	v_mfma_f32_16x16x32_bf16 v[114:117], v[162:165], v[138:141], v[114:117]
	v_mfma_f32_16x16x32_bf16 v[114:117], v[158:161], v[142:145], v[114:117]
	ds_read_b128 v[158:161], v156 offset:34048
	s_waitcnt lgkmcnt(0)
	v_mfma_f32_16x16x32_bf16 v[110:113], v[158:161], v[130:133], v[110:113]
	ds_read_b128 v[158:161], v156 offset:34112
	s_waitcnt lgkmcnt(0)
	v_mfma_f32_16x16x32_bf16 v[110:113], v[158:161], v[134:137], v[110:113]
	ds_read_b128 v[158:161], v156 offset:34176
	s_waitcnt lgkmcnt(0)
	v_mfma_f32_16x16x32_bf16 v[110:113], v[158:161], v[138:141], v[110:113]
	ds_read_b128 v[158:161], v156 offset:34240
	s_waitcnt lgkmcnt(0)
	v_mfma_f32_16x16x32_bf16 v[110:113], v[158:161], v[142:145], v[110:113]
	ds_read_b128 v[158:161], v156 offset:42688
	ds_read_b128 v[162:165], v156 offset:42624
	ds_read_b128 v[166:169], v156 offset:42560
	ds_read_b128 v[170:173], v156 offset:42496
	s_waitcnt lgkmcnt(0)
	v_mfma_f32_16x16x32_bf16 v[106:109], v[170:173], v[130:133], v[106:109]
	v_mfma_f32_16x16x32_bf16 v[106:109], v[166:169], v[134:137], v[106:109]
	v_mfma_f32_16x16x32_bf16 v[106:109], v[162:165], v[138:141], v[106:109]
	v_mfma_f32_16x16x32_bf16 v[106:109], v[158:161], v[142:145], v[106:109]
	ds_read_b128 v[158:161], v156 offset:50944
	s_waitcnt lgkmcnt(0)
	v_mfma_f32_16x16x32_bf16 v[102:105], v[158:161], v[130:133], v[102:105]
	ds_read_b128 v[158:161], v156 offset:51008
	s_waitcnt lgkmcnt(0)
	v_mfma_f32_16x16x32_bf16 v[102:105], v[158:161], v[134:137], v[102:105]
	ds_read_b128 v[158:161], v156 offset:51072
	s_waitcnt lgkmcnt(0)
; #define LAS __attribute__((address_space(3)))
; __device__ __forceinline__ f32x4 mfma16(bf16x8 a, bf16x8 b, f32x4 c) { return __builtin_amdgcn_mfma_f32_16x16x32_bf16(a, b, c, 0, 0, 0); }
; __device__ __forceinline__ void ret_out(const bf16* proj, const bf16* ST, bf16* mixed, const float* dexp, LAS unsigned char* lds, int vb, int nb, int tid_in0, int wave) {
;     ...
; #pragma unroll
;                     for (int v = 0; v < 16; ++v) {
;                         const LAS unsigned char* sp = Sx + (v * 16 + qi) * 528 + g * 16 + kh * 256;
; #pragma unroll
;                         for (int k4 = 0; k4 < 4; ++k4) o[v] = mfma16(*(const LAS bf16x8*)(sp + k4 * 64), qs[k4], o[v]);
;                         if ((v & 1) == 1) asm volatile("" ::: "memory");
;                     }
	v_mfma_f32_16x16x32_bf16 v[102:105], v[158:161], v[138:141], v[102:105]
	ds_read_b128 v[158:161], v156 offset:51136
	s_waitcnt lgkmcnt(0)
	v_mfma_f32_16x16x32_bf16 v[102:105], v[158:161], v[142:145], v[102:105]
	ds_read_b128 v[158:161], v156 offset:59584
	ds_read_b128 v[162:165], v156 offset:59520
	ds_read_b128 v[166:169], v156 offset:59456
	ds_read_b128 v[170:173], v156 offset:59392
	s_waitcnt lgkmcnt(0)
	v_mfma_f32_16x16x32_bf16 v[98:101], v[170:173], v[130:133], v[98:101]
	v_mfma_f32_16x16x32_bf16 v[98:101], v[166:169], v[134:137], v[98:101]
	v_mfma_f32_16x16x32_bf16 v[98:101], v[162:165], v[138:141], v[98:101]
	v_mfma_f32_16x16x32_bf16 v[98:101], v[158:161], v[142:145], v[98:101]
	ds_read_b128 v[156:159], v146
	s_waitcnt lgkmcnt(0)
	v_mfma_f32_16x16x32_bf16 v[94:97], v[156:159], v[130:133], v[94:97]
	ds_read_b128 v[156:159], v146 offset:64
	s_waitcnt lgkmcnt(0)
	v_mfma_f32_16x16x32_bf16 v[94:97], v[156:159], v[134:137], v[94:97]
	ds_read_b128 v[156:159], v146 offset:128
	s_waitcnt lgkmcnt(0)
	v_mfma_f32_16x16x32_bf16 v[94:97], v[156:159], v[138:141], v[94:97]
	ds_read_b128 v[156:159], v146 offset:192
	v_add_u32_e32 v146, v148, v154
	s_waitcnt lgkmcnt(0)
	v_mfma_f32_16x16x32_bf16 v[94:97], v[156:159], v[142:145], v[94:97]
	ds_read_b128 v[154:157], v146 offset:192
	ds_read_b128 v[158:161], v146 offset:128
	ds_read_b128 v[162:165], v146 offset:64
	ds_read_b128 v[166:169], v146
	v_add_u32_e32 v146, v148, v153
	s_waitcnt lgkmcnt(0)
	v_mfma_f32_16x16x32_bf16 v[90:93], v[166:169], v[130:133], v[90:93]
	v_mfma_f32_16x16x32_bf16 v[90:93], v[162:165], v[134:137], v[90:93]
	v_mfma_f32_16x16x32_bf16 v[90:93], v[158:161], v[138:141], v[90:93]
	v_mfma_f32_16x16x32_bf16 v[90:93], v[154:157], v[142:145], v[90:93]
	ds_read_b128 v[154:157], v146
	s_waitcnt lgkmcnt(0)
	v_mfma_f32_16x16x32_bf16 v[86:89], v[154:157], v[130:133], v[86:89]
	ds_read_b128 v[154:157], v146 offset:64
	s_waitcnt lgkmcnt(0)
	v_mfma_f32_16x16x32_bf16 v[86:89], v[154:157], v[134:137], v[86:89]
	ds_read_b128 v[154:157], v146 offset:128
	s_waitcnt lgkmcnt(0)
	v_mfma_f32_16x16x32_bf16 v[86:89], v[154:157], v[138:141], v[86:89]
	ds_read_b128 v[154:157], v146 offset:192
	v_add_u32_e32 v146, v148, v152
	s_waitcnt lgkmcnt(0)
	v_mfma_f32_16x16x32_bf16 v[86:89], v[154:157], v[142:145], v[86:89]
	ds_read_b128 v[152:155], v146 offset:192
	ds_read_b128 v[156:159], v146 offset:128
	ds_read_b128 v[160:163], v146 offset:64
	ds_read_b128 v[164:167], v146
	v_add_u32_e32 v146, v148, v151
	s_waitcnt lgkmcnt(0)
	v_mfma_f32_16x16x32_bf16 v[82:85], v[164:167], v[130:133], v[82:85]
	v_mfma_f32_16x16x32_bf16 v[82:85], v[160:163], v[134:137], v[82:85]
	v_mfma_f32_16x16x32_bf16 v[82:85], v[156:159], v[138:141], v[82:85]
	v_mfma_f32_16x16x32_bf16 v[82:85], v[152:155], v[142:145], v[82:85]
	ds_read_b128 v[152:155], v146
	s_waitcnt lgkmcnt(0)
	v_mfma_f32_16x16x32_bf16 v[78:81], v[152:155], v[130:133], v[78:81]
	ds_read_b128 v[152:155], v146 offset:64
	s_waitcnt lgkmcnt(0)
	v_mfma_f32_16x16x32_bf16 v[78:81], v[152:155], v[134:137], v[78:81]
	ds_read_b128 v[152:155], v146 offset:128
	s_waitcnt lgkmcnt(0)
	v_mfma_f32_16x16x32_bf16 v[78:81], v[152:155], v[138:141], v[78:81]
	ds_read_b128 v[152:155], v146 offset:192
	v_add_u32_e32 v146, v148, v150
	s_waitcnt lgkmcnt(0)
	v_mfma_f32_16x16x32_bf16 v[78:81], v[152:155], v[142:145], v[78:81]
	ds_read_b128 v[150:153], v146 offset:192
	ds_read_b128 v[154:157], v146 offset:128
	ds_read_b128 v[158:161], v146 offset:64
	ds_read_b128 v[162:165], v146
	v_add_u32_e32 v146, v148, v149
	s_waitcnt lgkmcnt(0)
	v_mfma_f32_16x16x32_bf16 v[74:77], v[162:165], v[130:133], v[74:77]
	v_mfma_f32_16x16x32_bf16 v[74:77], v[158:161], v[134:137], v[74:77]
	v_add_u32_e32 v158, v148, v147
	v_mfma_f32_16x16x32_bf16 v[74:77], v[154:157], v[138:141], v[74:77]
	v_mfma_f32_16x16x32_bf16 v[74:77], v[150:153], v[142:145], v[74:77]
	ds_read_b128 v[150:153], v146
	s_waitcnt lgkmcnt(0)
	v_mfma_f32_16x16x32_bf16 v[70:73], v[150:153], v[130:133], v[70:73]
	ds_read_b128 v[150:153], v146 offset:64
	s_waitcnt lgkmcnt(0)
	v_mfma_f32_16x16x32_bf16 v[70:73], v[150:153], v[134:137], v[70:73]
	ds_read_b128 v[150:153], v146 offset:128
	s_waitcnt lgkmcnt(0)
	v_mfma_f32_16x16x32_bf16 v[70:73], v[150:153], v[138:141], v[70:73]
	ds_read_b128 v[150:153], v146 offset:192
	s_waitcnt lgkmcnt(0)
	v_mfma_f32_16x16x32_bf16 v[70:73], v[150:153], v[142:145], v[70:73]
	ds_read_b128 v[146:149], v158 offset:192
	ds_read_b128 v[150:153], v158 offset:128
	ds_read_b128 v[154:157], v158 offset:64
	ds_read_b128 v[158:161], v158
	s_waitcnt lgkmcnt(0)
	v_mfma_f32_16x16x32_bf16 v[66:69], v[158:161], v[130:133], v[66:69]
	v_mfma_f32_16x16x32_bf16 v[66:69], v[154:157], v[134:137], v[66:69]
	v_mfma_f32_16x16x32_bf16 v[66:69], v[150:153], v[138:141], v[66:69]
	v_mfma_f32_16x16x32_bf16 v[66:69], v[146:149], v[142:145], v[66:69]
	s_branch .LBB0_833
